# e17: hand-written pooling phase - per 16-row block all loads batched, lane-distributed row scales (same math incl. fma pattern)
# speedup vs baseline: 1.0078x; 1.0078x over previous
; __device__ __forceinline__ float row_scale_any(const float* ssq, const float* ssqS, int row) { return row < MP ? pg8::row_scale(ssq, row) : sk::row_scale_s(ssqS, row - MP); }
; __device__ __forceinline__ f32x4 ldx4(const bf16* p) { const u32x2 w = *(const u32x2*)p; return (f32x4){__uint_as_float(w.x << 16), __uint_as_float(w.x & 0xffff0000u), __uint_as_float(w.y << 16), __uint_as_float(w.y & 0xffff0000u)}; }
; #define PHASE_SYNC(id) do { if ((id) != lo) xcd_barrier(bar); } while (0)
; template <int W> ...
;     const f32x4 gv = *(const f32x4*)(gain + c4);
;     f32x4 ring[16], wsum = {0.f, 0.f, 0.f, 0.f};
; #pragma unroll
;     for (int i = 0; i < 16; ++i) ring[i] = (f32x4){0.f, 0.f, 0.f, 0.f};
; #pragma unroll
;     for (int i = 1; i < 16; ++i) { const int r = -16 + i; f32x4 val = {0.f, 0.f, 0.f, 0.f};
;         if (histmode == 0) { const int row = xrow0 + r; const float rs = row_scale_any(ssq, ssqS, row); val = ldx4(X + (size_t)row * D + c4) * rs * gv; }
;         else if (histmode == 2) val = *(const f32x4*)(hist + (size_t)(r + 15) * D + c4);
;         wsum += val - ring[(i - W + 16) & 15]; ring[i] = val; }
; __global__ void __launch_bounds__(512, 2) fwd_kernel(Args a) {
;     ...
;             if (SITE(6) && PHASE_ON(base + 0)) { PHASE_SYNC(base + 0); PH_PTRS
;                 const float* gain = ap->in[I_NMIX] + (size_t)layer * D; const int c4 = tid * 4, grp = tid >> 7;
;                 for (int t = vcu; t < 256 + 16; t += G) {
;                     int xrow0, nt, pos0, hm, npf; const float* hist = nullptr; float* np = nullptr;
;                     if (t < 256) { xrow0 = 64 * t; nt = 64; pos0 = 64 * t; hm = t == 0 ? 1 : 0; npf = 49; if (t == 255) np = out + OFF_PL_P; }
;                     else { const int b = t - 256; xrow0 = MP + 16 * b; nt = 16; pos0 = 4096; hm = 2; hist = ap->in[I_SPL] + (size_t)b * 15 * D; npf = 1; np = out + OFF_PL_S + (size_t)b * 15 * D; }
;                     if (grp == 0) pool_tile<2>(XB, ssq_mix, sq_mix, gain, hist, hm, xrow0, nt, pos0, A0, np, npf, c4);
;                     else if (grp == 1) pool_tile<4>(XB, ssq_mix, sq_mix, gain, hist, hm, xrow0, nt, pos0, A0, np, npf, c4);
;                     else if (grp == 2) pool_tile<8>(XB, ssq_mix, sq_mix, gain, hist, hm, xrow0, nt, pos0, A0, np, npf, c4);
;                     else pool_tile<16>(XB, ssq_mix, sq_mix, gain, hist, hm, xrow0, nt, pos0, A0, np, npf, c4); } }
.LBB0_705:
	s_load_dwordx2 s[90:91], s[8:9], 0xf8
	s_load_dwordx2 s[0:1], s[8:9], 0x100
	s_load_dwordx2 s[4:5], s[8:9], 0x30
	v_readlane_b32 s6, v255, 14
	v_lshlrev_b32_e32 v4, 3, v0
	v_lshlrev_b32_e32 v5, 4, v0
	v_and_b32_e32 v2, 63, v0
	v_lshrrev_b32_e32 v6, 2, v2
	v_lshlrev_b32_e32 v6, 5, v6
	v_lshlrev_b32_e32 v7, 3, v6
	v_and_b32_e32 v19, 3, v2
	v_lshl_add_u32 v7, v19, 6, v7
	v_readfirstlane_b32 s10, v0
	v_mov_b32_e32 v17, 0x358637bd
	s_nop 1
	s_lshr_b32 s10, s10, 7
	s_lshl_b32 s15, 2, s10
	s_sub_i32 s12, 0x7e, s10
	s_lshl_b32 s12, s12, 23
	v_mov_b32_e32 v16, s12
	s_cmp_eq_u32 s15, 2
	s_cselect_b64 s[58:59], -1, 0
	s_cmp_eq_u32 s15, 4
	s_cselect_b64 s[62:63], -1, 0
	s_cmp_eq_u32 s15, 8
	s_cselect_b64 s[64:65], -1, 0
	s_mul_i32 s66, s6, 0x104000
	s_add_u32 s66, s66, 0x41800000
	s_lshl_b32 s67, s6, 17
	s_add_u32 s67, s67, 0x41e00000
	s_lshl_b32 s10, s6, 13
	s_waitcnt lgkmcnt(0)
	s_add_u32 s4, s4, s10
	s_addc_u32 s5, s5, 0
	global_load_dwordx4 v[8:11], v5, s[4:5]
.Lpool_tile:
	s_cmpk_gt_i32 s21, 0xff
	s_cbranch_scc1 .Lpool_sample
	s_lshl_b32 s77, s21, 6
	s_mov_b32 s43, s77
	s_mov_b32 s45, 4
	s_mov_b32 s49, 0
	s_mov_b32 s37, 0
	s_cmpk_lg_i32 s21, 0xff
	s_cbranch_scc1 .Lpool_nonp
	s_add_u32 s86, s90, 0xa400000
	s_addc_u32 s87, s91, 0
	s_mov_b32 s37, 1
.Lpool_nonp:
	v_mov_b32_e32 v32, 0
	v_mov_b32_e32 v33, 0
	v_mov_b32_e32 v34, 0
	v_mov_b32_e32 v35, 0
	v_mov_b32_e32 v36, 0
	v_mov_b32_e32 v37, 0
	v_mov_b32_e32 v38, 0
	v_mov_b32_e32 v39, 0
	v_mov_b32_e32 v40, 0
	v_mov_b32_e32 v41, 0
	v_mov_b32_e32 v42, 0
	v_mov_b32_e32 v43, 0
	v_mov_b32_e32 v44, 0
	v_mov_b32_e32 v45, 0
	v_mov_b32_e32 v46, 0
	v_mov_b32_e32 v47, 0
	v_mov_b32_e32 v48, 0
	v_mov_b32_e32 v49, 0
	v_mov_b32_e32 v50, 0
	v_mov_b32_e32 v51, 0
	v_mov_b32_e32 v52, 0
	v_mov_b32_e32 v53, 0
	v_mov_b32_e32 v54, 0
	v_mov_b32_e32 v55, 0
	v_mov_b32_e32 v56, 0
	v_mov_b32_e32 v57, 0
	v_mov_b32_e32 v58, 0
	v_mov_b32_e32 v59, 0
	v_mov_b32_e32 v60, 0
	v_mov_b32_e32 v61, 0
	v_mov_b32_e32 v62, 0
	v_mov_b32_e32 v63, 0
	v_mov_b32_e32 v64, 0
	v_mov_b32_e32 v65, 0
	v_mov_b32_e32 v66, 0
	v_mov_b32_e32 v67, 0
	v_mov_b32_e32 v68, 0
	v_mov_b32_e32 v69, 0
	v_mov_b32_e32 v70, 0
	v_mov_b32_e32 v71, 0
	v_mov_b32_e32 v72, 0
	v_mov_b32_e32 v73, 0
	v_mov_b32_e32 v74, 0
	v_mov_b32_e32 v75, 0
	v_mov_b32_e32 v76, 0
	v_mov_b32_e32 v77, 0
	v_mov_b32_e32 v78, 0
	v_mov_b32_e32 v79, 0
	v_mov_b32_e32 v80, 0
	v_mov_b32_e32 v81, 0
	v_mov_b32_e32 v82, 0
	v_mov_b32_e32 v83, 0
	v_mov_b32_e32 v84, 0
	v_mov_b32_e32 v85, 0
	v_mov_b32_e32 v86, 0
	v_mov_b32_e32 v87, 0
	v_mov_b32_e32 v88, 0
	v_mov_b32_e32 v89, 0
	v_mov_b32_e32 v90, 0
	v_mov_b32_e32 v91, 0
	v_mov_b32_e32 v92, 0
	v_mov_b32_e32 v93, 0
	v_mov_b32_e32 v94, 0
	v_mov_b32_e32 v95, 0
	v_mov_b32_e32 v12, 0
	v_mov_b32_e32 v13, 0
	v_mov_b32_e32 v14, 0
	v_mov_b32_e32 v15, 0
	s_mov_b32 s41, 0
	s_cmp_eq_u32 s21, 0
	s_cbranch_scc1 .Lpool_blk
	s_mov_b32 s41, 1
	s_sub_i32 s77, s77, 16
	s_branch .Lpool_blk
.Lpool_sample:
	s_load_dwordx2 s[78:79], s[8:9], 0x18
	s_add_i32 s10, s21, 0xffffff00
	s_lshl_b32 s77, s10, 4
	s_add_i32 s77, s77, 0x4000
	s_movk_i32 s43, 0x1000
	s_mov_b32 s45, 1
	s_mov_b32 s49, 1
	s_mov_b32 s37, 1
	s_mov_b32 s41, 0
	s_mul_i32 s10, s10, 0x1e000
	s_add_u32 s86, s90, 0xa41e000
	s_addc_u32 s87, s91, 0
	s_add_u32 s86, s86, s10
	s_addc_u32 s87, s87, 0
	s_waitcnt lgkmcnt(0)
	s_add_u32 s78, s78, s10
	s_addc_u32 s79, s79, 0
	global_load_dwordx4 v[36:39], v5, s[78:79]
	s_add_u32 s78, s78, 0x2000
	s_addc_u32 s79, s79, 0
	global_load_dwordx4 v[40:43], v5, s[78:79]
	s_add_u32 s78, s78, 0x2000
	s_addc_u32 s79, s79, 0
	global_load_dwordx4 v[44:47], v5, s[78:79]
	s_add_u32 s78, s78, 0x2000
	s_addc_u32 s79, s79, 0
	global_load_dwordx4 v[48:51], v5, s[78:79]
	s_add_u32 s78, s78, 0x2000
	s_addc_u32 s79, s79, 0
	global_load_dwordx4 v[52:55], v5, s[78:79]
	s_add_u32 s78, s78, 0x2000
	s_addc_u32 s79, s79, 0
	global_load_dwordx4 v[56:59], v5, s[78:79]
	s_add_u32 s78, s78, 0x2000
	s_addc_u32 s79, s79, 0
	global_load_dwordx4 v[60:63], v5, s[78:79]
	s_add_u32 s78, s78, 0x2000
	s_addc_u32 s79, s79, 0
	global_load_dwordx4 v[64:67], v5, s[78:79]
	s_add_u32 s78, s78, 0x2000
	s_addc_u32 s79, s79, 0
	global_load_dwordx4 v[68:71], v5, s[78:79]
	s_add_u32 s78, s78, 0x2000
	s_addc_u32 s79, s79, 0
	global_load_dwordx4 v[72:75], v5, s[78:79]
	s_add_u32 s78, s78, 0x2000
	s_addc_u32 s79, s79, 0
	global_load_dwordx4 v[76:79], v5, s[78:79]
	s_add_u32 s78, s78, 0x2000
	s_addc_u32 s79, s79, 0
	global_load_dwordx4 v[80:83], v5, s[78:79]
	s_add_u32 s78, s78, 0x2000
	s_addc_u32 s79, s79, 0
	global_load_dwordx4 v[84:87], v5, s[78:79]
	s_add_u32 s78, s78, 0x2000
	s_addc_u32 s79, s79, 0
	global_load_dwordx4 v[88:91], v5, s[78:79]
	s_add_u32 s78, s78, 0x2000
	s_addc_u32 s79, s79, 0
	global_load_dwordx4 v[92:95], v5, s[78:79]
	v_mov_b32_e32 v32, 0
	v_mov_b32_e32 v33, 0
	v_mov_b32_e32 v34, 0
	v_mov_b32_e32 v35, 0
	v_mov_b32_e32 v12, 0
	v_mov_b32_e32 v13, 0
	v_mov_b32_e32 v14, 0
	v_mov_b32_e32 v15, 0
	s_waitcnt vmcnt(0)
; __device__ __forceinline__ float row_scale_any(const float* ssq, const float* ssqS, int row) { return row < MP ? pg8::row_scale(ssq, row) : sk::row_scale_s(ssqS, row - MP); }
; __device__ __forceinline__ f32x4 ldx4(const bf16* p) { const u32x2 w = *(const u32x2*)p; return (f32x4){__uint_as_float(w.x << 16), __uint_as_float(w.x & 0xffff0000u), __uint_as_float(w.y << 16), __uint_as_float(w.y & 0xffff0000u)}; }
; template <int W> ...
;     const f32x4 gv = *(const f32x4*)(gain + c4);
;     f32x4 ring[16], wsum = {0.f, 0.f, 0.f, 0.f};
; #pragma unroll
;     for (int i = 0; i < 16; ++i) ring[i] = (f32x4){0.f, 0.f, 0.f, 0.f};
; #pragma unroll
;     for (int i = 1; i < 16; ++i) { const int r = -16 + i; f32x4 val = {0.f, 0.f, 0.f, 0.f};
;         if (histmode == 0) { const int row = xrow0 + r; const float rs = row_scale_any(ssq, ssqS, row); val = ldx4(X + (size_t)row * D + c4) * rs * gv; }
;         else if (histmode == 2) val = *(const f32x4*)(hist + (size_t)(r + 15) * D + c4);
;         wsum += val - ring[(i - W + 16) & 15]; ring[i] = val; }
	v_mov_b32_e32 v24, 0
	v_mov_b32_e32 v25, 0
	v_mov_b32_e32 v26, 0
	v_mov_b32_e32 v27, 0
	v_pk_add_f32 v[28:29], v[36:37], v[24:25] neg_lo:[0,1] neg_hi:[0,1]
	v_pk_add_f32 v[30:31], v[38:39], v[26:27] neg_lo:[0,1] neg_hi:[0,1]
	v_pk_add_f32 v[12:13], v[12:13], v[28:29]
	v_pk_add_f32 v[14:15], v[14:15], v[30:31]
	v_cndmask_b32_e64 v24, v3, v32, s[58:59]
	v_cndmask_b32_e64 v25, v3, v33, s[58:59]
	v_cndmask_b32_e64 v26, v3, v34, s[58:59]
	v_cndmask_b32_e64 v27, v3, v35, s[58:59]
	v_pk_add_f32 v[28:29], v[40:41], v[24:25] neg_lo:[0,1] neg_hi:[0,1]
	v_pk_add_f32 v[30:31], v[42:43], v[26:27] neg_lo:[0,1] neg_hi:[0,1]
	v_pk_add_f32 v[12:13], v[12:13], v[28:29]
	v_pk_add_f32 v[14:15], v[14:15], v[30:31]
	v_cndmask_b32_e64 v24, v3, v36, s[58:59]
	v_cndmask_b32_e64 v25, v3, v37, s[58:59]
	v_cndmask_b32_e64 v26, v3, v38, s[58:59]
	v_cndmask_b32_e64 v27, v3, v39, s[58:59]
	v_pk_add_f32 v[28:29], v[44:45], v[24:25] neg_lo:[0,1] neg_hi:[0,1]
	v_pk_add_f32 v[30:31], v[46:47], v[26:27] neg_lo:[0,1] neg_hi:[0,1]
	v_pk_add_f32 v[12:13], v[12:13], v[28:29]
	v_pk_add_f32 v[14:15], v[14:15], v[30:31]
	v_cndmask_b32_e64 v24, v3, v32, s[62:63]
	v_cndmask_b32_e64 v24, v24, v40, s[58:59]
	v_cndmask_b32_e64 v25, v3, v33, s[62:63]
	v_cndmask_b32_e64 v25, v25, v41, s[58:59]
	v_cndmask_b32_e64 v26, v3, v34, s[62:63]
	v_cndmask_b32_e64 v26, v26, v42, s[58:59]
	v_cndmask_b32_e64 v27, v3, v35, s[62:63]
	v_cndmask_b32_e64 v27, v27, v43, s[58:59]
	v_pk_add_f32 v[28:29], v[48:49], v[24:25] neg_lo:[0,1] neg_hi:[0,1]
	v_pk_add_f32 v[30:31], v[50:51], v[26:27] neg_lo:[0,1] neg_hi:[0,1]
	v_pk_add_f32 v[12:13], v[12:13], v[28:29]
	v_pk_add_f32 v[14:15], v[14:15], v[30:31]
	v_cndmask_b32_e64 v24, v3, v36, s[62:63]
	v_cndmask_b32_e64 v24, v24, v44, s[58:59]
	v_cndmask_b32_e64 v25, v3, v37, s[62:63]
	v_cndmask_b32_e64 v25, v25, v45, s[58:59]
	v_cndmask_b32_e64 v26, v3, v38, s[62:63]
	v_cndmask_b32_e64 v26, v26, v46, s[58:59]
	v_cndmask_b32_e64 v27, v3, v39, s[62:63]
	v_cndmask_b32_e64 v27, v27, v47, s[58:59]
	v_pk_add_f32 v[28:29], v[52:53], v[24:25] neg_lo:[0,1] neg_hi:[0,1]
	v_pk_add_f32 v[30:31], v[54:55], v[26:27] neg_lo:[0,1] neg_hi:[0,1]
	v_pk_add_f32 v[12:13], v[12:13], v[28:29]
	v_pk_add_f32 v[14:15], v[14:15], v[30:31]
	v_cndmask_b32_e64 v24, v3, v40, s[62:63]
	v_cndmask_b32_e64 v24, v24, v48, s[58:59]
	v_cndmask_b32_e64 v25, v3, v41, s[62:63]
	v_cndmask_b32_e64 v25, v25, v49, s[58:59]
	v_cndmask_b32_e64 v26, v3, v42, s[62:63]
	v_cndmask_b32_e64 v26, v26, v50, s[58:59]
	v_cndmask_b32_e64 v27, v3, v43, s[62:63]
	v_cndmask_b32_e64 v27, v27, v51, s[58:59]
	v_pk_add_f32 v[28:29], v[56:57], v[24:25] neg_lo:[0,1] neg_hi:[0,1]
	v_pk_add_f32 v[30:31], v[58:59], v[26:27] neg_lo:[0,1] neg_hi:[0,1]
	v_pk_add_f32 v[12:13], v[12:13], v[28:29]
	v_pk_add_f32 v[14:15], v[14:15], v[30:31]
	v_cndmask_b32_e64 v24, v3, v44, s[62:63]
	v_cndmask_b32_e64 v24, v24, v52, s[58:59]
	v_cndmask_b32_e64 v25, v3, v45, s[62:63]
	v_cndmask_b32_e64 v25, v25, v53, s[58:59]
	v_cndmask_b32_e64 v26, v3, v46, s[62:63]
	v_cndmask_b32_e64 v26, v26, v54, s[58:59]
	v_cndmask_b32_e64 v27, v3, v47, s[62:63]
	v_cndmask_b32_e64 v27, v27, v55, s[58:59]
	v_pk_add_f32 v[28:29], v[60:61], v[24:25] neg_lo:[0,1] neg_hi:[0,1]
	v_pk_add_f32 v[30:31], v[62:63], v[26:27] neg_lo:[0,1] neg_hi:[0,1]
	v_pk_add_f32 v[12:13], v[12:13], v[28:29]
	v_pk_add_f32 v[14:15], v[14:15], v[30:31]
	v_cndmask_b32_e64 v24, v3, v32, s[64:65]
	v_cndmask_b32_e64 v24, v24, v48, s[62:63]
	v_cndmask_b32_e64 v24, v24, v56, s[58:59]
	v_cndmask_b32_e64 v25, v3, v33, s[64:65]
	v_cndmask_b32_e64 v25, v25, v49, s[62:63]
	v_cndmask_b32_e64 v25, v25, v57, s[58:59]
	v_cndmask_b32_e64 v26, v3, v34, s[64:65]
	v_cndmask_b32_e64 v26, v26, v50, s[62:63]
	v_cndmask_b32_e64 v26, v26, v58, s[58:59]
	v_cndmask_b32_e64 v27, v3, v35, s[64:65]
	v_cndmask_b32_e64 v27, v27, v51, s[62:63]
	v_cndmask_b32_e64 v27, v27, v59, s[58:59]
	v_pk_add_f32 v[28:29], v[64:65], v[24:25] neg_lo:[0,1] neg_hi:[0,1]
	v_pk_add_f32 v[30:31], v[66:67], v[26:27] neg_lo:[0,1] neg_hi:[0,1]
	v_pk_add_f32 v[12:13], v[12:13], v[28:29]
	v_pk_add_f32 v[14:15], v[14:15], v[30:31]
	v_cndmask_b32_e64 v24, v3, v36, s[64:65]
	v_cndmask_b32_e64 v24, v24, v52, s[62:63]
	v_cndmask_b32_e64 v24, v24, v60, s[58:59]
	v_cndmask_b32_e64 v25, v3, v37, s[64:65]
	v_cndmask_b32_e64 v25, v25, v53, s[62:63]
	v_cndmask_b32_e64 v25, v25, v61, s[58:59]
	v_cndmask_b32_e64 v26, v3, v38, s[64:65]
	v_cndmask_b32_e64 v26, v26, v54, s[62:63]
	v_cndmask_b32_e64 v26, v26, v62, s[58:59]
	v_cndmask_b32_e64 v27, v3, v39, s[64:65]
	v_cndmask_b32_e64 v27, v27, v55, s[62:63]
	v_cndmask_b32_e64 v27, v27, v63, s[58:59]
	v_pk_add_f32 v[28:29], v[68:69], v[24:25] neg_lo:[0,1] neg_hi:[0,1]
	v_pk_add_f32 v[30:31], v[70:71], v[26:27] neg_lo:[0,1] neg_hi:[0,1]
	v_pk_add_f32 v[12:13], v[12:13], v[28:29]
	v_pk_add_f32 v[14:15], v[14:15], v[30:31]
	v_cndmask_b32_e64 v24, v3, v40, s[64:65]
	v_cndmask_b32_e64 v24, v24, v56, s[62:63]
	v_cndmask_b32_e64 v24, v24, v64, s[58:59]
	v_cndmask_b32_e64 v25, v3, v41, s[64:65]
	v_cndmask_b32_e64 v25, v25, v57, s[62:63]
	v_cndmask_b32_e64 v25, v25, v65, s[58:59]
	v_cndmask_b32_e64 v26, v3, v42, s[64:65]
	v_cndmask_b32_e64 v26, v26, v58, s[62:63]
	v_cndmask_b32_e64 v26, v26, v66, s[58:59]
	v_cndmask_b32_e64 v27, v3, v43, s[64:65]
	v_cndmask_b32_e64 v27, v27, v59, s[62:63]
	v_cndmask_b32_e64 v27, v27, v67, s[58:59]
	v_pk_add_f32 v[28:29], v[72:73], v[24:25] neg_lo:[0,1] neg_hi:[0,1]
	v_pk_add_f32 v[30:31], v[74:75], v[26:27] neg_lo:[0,1] neg_hi:[0,1]
	v_pk_add_f32 v[12:13], v[12:13], v[28:29]
	v_pk_add_f32 v[14:15], v[14:15], v[30:31]
	v_cndmask_b32_e64 v24, v3, v44, s[64:65]
	v_cndmask_b32_e64 v24, v24, v60, s[62:63]
; __device__ __forceinline__ float row_scale_any(const float* ssq, const float* ssqS, int row) { return row < MP ? pg8::row_scale(ssq, row) : sk::row_scale_s(ssqS, row - MP); }
; __device__ __forceinline__ f32x4 ldx4(const bf16* p) { const u32x2 w = *(const u32x2*)p; return (f32x4){__uint_as_float(w.x << 16), __uint_as_float(w.x & 0xffff0000u), __uint_as_float(w.y << 16), __uint_as_float(w.y & 0xffff0000u)}; }
; __device__ __forceinline__ float row_scale(const float* ssq, int row) { const f32x4 a = *(const f32x4*)(ssq + (size_t)row * 8), b = *(const f32x4*)(ssq + (size_t)row * 8 + 4);
;     return __builtin_amdgcn_rsqf((((a[0] + a[1]) + (a[2] + a[3])) + ((b[0] + b[1]) + (b[2] + b[3]))) * (1.0f / 2048.0f) + 1e-6f); }
; template <int W> ...
;     ...
;     for (int i = 1; i < 16; ++i) { const int r = -16 + i; f32x4 val = {0.f, 0.f, 0.f, 0.f};
;         if (histmode == 0) { const int row = xrow0 + r; const float rs = row_scale_any(ssq, ssqS, row); val = ldx4(X + (size_t)row * D + c4) * rs * gv; }
;         else if (histmode == 2) val = *(const f32x4*)(hist + (size_t)(r + 15) * D + c4);
;         wsum += val - ring[(i - W + 16) & 15]; ring[i] = val; }
;     for (int blk = 0; blk < nt / 16; ++blk) {
; #pragma unroll
;         for (int i = 0; i < 16; ++i) { const int r = 16 * blk + i, row = xrow0 + r; const float rs = row_scale_any(ssq, ssqS, row);
;             const f32x4 val = ldx4(X + (size_t)row * D + c4) * rs * gv;
	v_cndmask_b32_e64 v24, v24, v68, s[58:59]
	v_cndmask_b32_e64 v25, v3, v45, s[64:65]
	v_cndmask_b32_e64 v25, v25, v61, s[62:63]
	v_cndmask_b32_e64 v25, v25, v69, s[58:59]
	v_cndmask_b32_e64 v26, v3, v46, s[64:65]
	v_cndmask_b32_e64 v26, v26, v62, s[62:63]
	v_cndmask_b32_e64 v26, v26, v70, s[58:59]
	v_cndmask_b32_e64 v27, v3, v47, s[64:65]
	v_cndmask_b32_e64 v27, v27, v63, s[62:63]
	v_cndmask_b32_e64 v27, v27, v71, s[58:59]
	v_pk_add_f32 v[28:29], v[76:77], v[24:25] neg_lo:[0,1] neg_hi:[0,1]
	v_pk_add_f32 v[30:31], v[78:79], v[26:27] neg_lo:[0,1] neg_hi:[0,1]
	v_pk_add_f32 v[12:13], v[12:13], v[28:29]
	v_pk_add_f32 v[14:15], v[14:15], v[30:31]
	v_cndmask_b32_e64 v24, v3, v48, s[64:65]
	v_cndmask_b32_e64 v24, v24, v64, s[62:63]
	v_cndmask_b32_e64 v24, v24, v72, s[58:59]
	v_cndmask_b32_e64 v25, v3, v49, s[64:65]
	v_cndmask_b32_e64 v25, v25, v65, s[62:63]
	v_cndmask_b32_e64 v25, v25, v73, s[58:59]
	v_cndmask_b32_e64 v26, v3, v50, s[64:65]
	v_cndmask_b32_e64 v26, v26, v66, s[62:63]
	v_cndmask_b32_e64 v26, v26, v74, s[58:59]
	v_cndmask_b32_e64 v27, v3, v51, s[64:65]
	v_cndmask_b32_e64 v27, v27, v67, s[62:63]
	v_cndmask_b32_e64 v27, v27, v75, s[58:59]
	v_pk_add_f32 v[28:29], v[80:81], v[24:25] neg_lo:[0,1] neg_hi:[0,1]
	v_pk_add_f32 v[30:31], v[82:83], v[26:27] neg_lo:[0,1] neg_hi:[0,1]
	v_pk_add_f32 v[12:13], v[12:13], v[28:29]
	v_pk_add_f32 v[14:15], v[14:15], v[30:31]
	v_cndmask_b32_e64 v24, v3, v52, s[64:65]
	v_cndmask_b32_e64 v24, v24, v68, s[62:63]
	v_cndmask_b32_e64 v24, v24, v76, s[58:59]
	v_cndmask_b32_e64 v25, v3, v53, s[64:65]
	v_cndmask_b32_e64 v25, v25, v69, s[62:63]
	v_cndmask_b32_e64 v25, v25, v77, s[58:59]
	v_cndmask_b32_e64 v26, v3, v54, s[64:65]
	v_cndmask_b32_e64 v26, v26, v70, s[62:63]
	v_cndmask_b32_e64 v26, v26, v78, s[58:59]
	v_cndmask_b32_e64 v27, v3, v55, s[64:65]
	v_cndmask_b32_e64 v27, v27, v71, s[62:63]
	v_cndmask_b32_e64 v27, v27, v79, s[58:59]
	v_pk_add_f32 v[28:29], v[84:85], v[24:25] neg_lo:[0,1] neg_hi:[0,1]
	v_pk_add_f32 v[30:31], v[86:87], v[26:27] neg_lo:[0,1] neg_hi:[0,1]
	v_pk_add_f32 v[12:13], v[12:13], v[28:29]
	v_pk_add_f32 v[14:15], v[14:15], v[30:31]
	v_cndmask_b32_e64 v24, v3, v56, s[64:65]
	v_cndmask_b32_e64 v24, v24, v72, s[62:63]
	v_cndmask_b32_e64 v24, v24, v80, s[58:59]
	v_cndmask_b32_e64 v25, v3, v57, s[64:65]
	v_cndmask_b32_e64 v25, v25, v73, s[62:63]
	v_cndmask_b32_e64 v25, v25, v81, s[58:59]
	v_cndmask_b32_e64 v26, v3, v58, s[64:65]
	v_cndmask_b32_e64 v26, v26, v74, s[62:63]
	v_cndmask_b32_e64 v26, v26, v82, s[58:59]
	v_cndmask_b32_e64 v27, v3, v59, s[64:65]
	v_cndmask_b32_e64 v27, v27, v75, s[62:63]
	v_cndmask_b32_e64 v27, v27, v83, s[58:59]
	v_pk_add_f32 v[28:29], v[88:89], v[24:25] neg_lo:[0,1] neg_hi:[0,1]
	v_pk_add_f32 v[30:31], v[90:91], v[26:27] neg_lo:[0,1] neg_hi:[0,1]
	v_pk_add_f32 v[12:13], v[12:13], v[28:29]
	v_pk_add_f32 v[14:15], v[14:15], v[30:31]
	v_cndmask_b32_e64 v24, v3, v60, s[64:65]
	v_cndmask_b32_e64 v24, v24, v76, s[62:63]
	v_cndmask_b32_e64 v24, v24, v84, s[58:59]
	v_cndmask_b32_e64 v25, v3, v61, s[64:65]
	v_cndmask_b32_e64 v25, v25, v77, s[62:63]
	v_cndmask_b32_e64 v25, v25, v85, s[58:59]
	v_cndmask_b32_e64 v26, v3, v62, s[64:65]
	v_cndmask_b32_e64 v26, v26, v78, s[62:63]
	v_cndmask_b32_e64 v26, v26, v86, s[58:59]
	v_cndmask_b32_e64 v27, v3, v63, s[64:65]
	v_cndmask_b32_e64 v27, v27, v79, s[62:63]
	v_cndmask_b32_e64 v27, v27, v87, s[58:59]
	v_pk_add_f32 v[28:29], v[92:93], v[24:25] neg_lo:[0,1] neg_hi:[0,1]
	v_pk_add_f32 v[30:31], v[94:95], v[26:27] neg_lo:[0,1] neg_hi:[0,1]
	v_pk_add_f32 v[12:13], v[12:13], v[28:29]
	v_pk_add_f32 v[14:15], v[14:15], v[30:31]
.Lpool_blk:
	s_lshl_b32 s10, s77, 12
	s_add_u32 s4, s0, s10
	s_addc_u32 s5, s1, 0
	s_add_u32 s2, s4, 0x24400000
	s_addc_u32 s3, s5, 0
	s_add_u32 s4, s4, 0x20200000
	s_addc_u32 s5, s5, 0
	s_cmp_eq_u32 s49, 1
	s_cbranch_scc1 .Lpool_ssq_s
	s_lshl_b32 s10, s77, 5
	s_add_u32 s10, s10, s66
	s_add_u32 s98, s0, s10
	s_addc_u32 s99, s1, 0
	global_load_dwordx4 v[96:99], v6, s[98:99]
	global_load_dwordx4 v[100:103], v6, s[98:99] offset:16
	s_branch .Lpool_xld
.Lpool_ssq_s:
	s_add_i32 s10, s77, 0xffffc000
	s_lshl_b32 s10, s10, 8
	s_add_u32 s10, s10, s67
	s_add_u32 s98, s0, s10
	s_addc_u32 s99, s1, 0
	global_load_dwordx4 v[96:99], v7, s[98:99]
	global_load_dwordx4 v[100:103], v7, s[98:99] offset:16
	global_load_dwordx4 v[104:107], v7, s[98:99] offset:32
	global_load_dwordx4 v[108:111], v7, s[98:99] offset:48
.Lpool_xld:
	global_load_dwordx2 v[208:209], v4, s[4:5]
	s_add_u32 s4, s4, 0x1000
	s_addc_u32 s5, s5, 0
	global_load_dwordx2 v[210:211], v4, s[4:5]
	s_add_u32 s4, s4, 0x1000
	s_addc_u32 s5, s5, 0
	global_load_dwordx2 v[212:213], v4, s[4:5]
	s_add_u32 s4, s4, 0x1000
	s_addc_u32 s5, s5, 0
	global_load_dwordx2 v[214:215], v4, s[4:5]
	s_add_u32 s4, s4, 0x1000
	s_addc_u32 s5, s5, 0
	global_load_dwordx2 v[216:217], v4, s[4:5]
	s_add_u32 s4, s4, 0x1000
	s_addc_u32 s5, s5, 0
	global_load_dwordx2 v[218:219], v4, s[4:5]
	s_add_u32 s4, s4, 0x1000
	s_addc_u32 s5, s5, 0
	global_load_dwordx2 v[220:221], v4, s[4:5]
	s_add_u32 s4, s4, 0x1000
	s_addc_u32 s5, s5, 0
	global_load_dwordx2 v[222:223], v4, s[4:5]
	s_add_u32 s4, s4, 0x1000
	s_addc_u32 s5, s5, 0
	global_load_dwordx2 v[224:225], v4, s[4:5]
	s_add_u32 s4, s4, 0x1000
	s_addc_u32 s5, s5, 0
	global_load_dwordx2 v[226:227], v4, s[4:5]
	s_add_u32 s4, s4, 0x1000
	s_addc_u32 s5, s5, 0
	global_load_dwordx2 v[228:229], v4, s[4:5]
	s_add_u32 s4, s4, 0x1000
	s_addc_u32 s5, s5, 0
	global_load_dwordx2 v[230:231], v4, s[4:5]
	s_add_u32 s4, s4, 0x1000
	s_addc_u32 s5, s5, 0
	global_load_dwordx2 v[232:233], v4, s[4:5]
	s_add_u32 s4, s4, 0x1000
	s_addc_u32 s5, s5, 0
	global_load_dwordx2 v[234:235], v4, s[4:5]
	s_add_u32 s4, s4, 0x1000
	s_addc_u32 s5, s5, 0
	global_load_dwordx2 v[236:237], v4, s[4:5]
	s_add_u32 s4, s4, 0x1000
	s_addc_u32 s5, s5, 0
	global_load_dwordx2 v[238:239], v4, s[4:5]
	s_waitcnt vmcnt(0)
	s_cmp_eq_u32 s49, 1
	s_cbranch_scc1 .Lpool_rs_s
	v_add_f32_e32 v18, v96, v97
	v_add_f32_e32 v19, v98, v99
	v_add_f32_e32 v18, v18, v19
	v_add_f32_e32 v19, v100, v101
	v_add_f32_e32 v2, v102, v103
	v_add_f32_e32 v19, v19, v2
	v_add_f32_e32 v18, v18, v19
	s_branch .Lpool_rs_done
; __device__ __forceinline__ unsigned cvt_pk_bf16(float lo, float hi) { unsigned r; asm volatile("v_cvt_pk_bf16_f32 %0, %1, %2" : "=v"(r) : "v"(lo), "v"(hi)); return r; }
; __device__ __forceinline__ float row_scale_any(const float* ssq, const float* ssqS, int row) { return row < MP ? pg8::row_scale(ssq, row) : sk::row_scale_s(ssqS, row - MP); }
; __device__ __forceinline__ f32x4 ldx4(const bf16* p) { const u32x2 w = *(const u32x2*)p; return (f32x4){__uint_as_float(w.x << 16), __uint_as_float(w.x & 0xffff0000u), __uint_as_float(w.y << 16), __uint_as_float(w.y & 0xffff0000u)}; }
; #pragma unroll
;     for (int i = 0; i < 16; ++i) { const f32x4 a = *(const f32x4*)(ssqS + (size_t)row * 64 + 4 * i); t += (a[0] + a[1]) + (a[2] + a[3]); }
;     return __builtin_amdgcn_rsqf(t * (1.0f / 2048.0f) + 1e-6f); }
; template <int W> ...
;     ...
;         for (int i = 0; i < 16; ++i) { const int r = 16 * blk + i, row = xrow0 + r; const float rs = row_scale_any(ssq, ssqS, row);
;             const f32x4 val = ldx4(X + (size_t)row * D + c4) * rs * gv;
;             wsum += val - ring[(i - W + 16) & 15]; ring[i] = val;
;             const int cnt = (pos0 + r + 1) < W ? (pos0 + r + 1) : W; const float ic = 1.0f / (float)cnt;
;             const f32x4 pv = wsum * ic - val;
;             u32x2 pw; pw.x = cvt_pk_bf16(pv[0], pv[1]); pw.y = cvt_pk_bf16(pv[2], pv[3]);
;             *(u32x2*)(P + (size_t)row * D + c4) = pw;
;             if (newpool && r >= np_first) *(f32x4*)(newpool + (size_t)(r - np_first) * D + c4) = val; }
.Lpool_rs_s:
	v_add_f32_e32 v96, v96, v97
	v_add_f32_e32 v98, v98, v99
	v_add_f32_e32 v96, v96, v98
	v_add_f32_e32 v100, v100, v101
	v_add_f32_e32 v102, v102, v103
	v_add_f32_e32 v100, v100, v102
	v_add_f32_e32 v104, v104, v105
	v_add_f32_e32 v106, v106, v107
	v_add_f32_e32 v104, v104, v106
	v_add_f32_e32 v108, v108, v109
	v_add_f32_e32 v110, v110, v111
	v_add_f32_e32 v108, v108, v110
	v_mov_b32_e32 v18, 0
	s_nop 1
	v_add_f32_dpp v18, v96, v18 quad_perm:[0,0,0,0] row_mask:0xf bank_mask:0xf
	s_nop 1
	v_add_f32_dpp v18, v100, v18 quad_perm:[0,0,0,0] row_mask:0xf bank_mask:0xf
	s_nop 1
	v_add_f32_dpp v18, v104, v18 quad_perm:[0,0,0,0] row_mask:0xf bank_mask:0xf
	s_nop 1
	v_add_f32_dpp v18, v108, v18 quad_perm:[0,0,0,0] row_mask:0xf bank_mask:0xf
	s_nop 1
	v_add_f32_dpp v18, v96, v18 quad_perm:[1,1,1,1] row_mask:0xf bank_mask:0xf
	s_nop 1
	v_add_f32_dpp v18, v100, v18 quad_perm:[1,1,1,1] row_mask:0xf bank_mask:0xf
	s_nop 1
	v_add_f32_dpp v18, v104, v18 quad_perm:[1,1,1,1] row_mask:0xf bank_mask:0xf
	s_nop 1
	v_add_f32_dpp v18, v108, v18 quad_perm:[1,1,1,1] row_mask:0xf bank_mask:0xf
	s_nop 1
	v_add_f32_dpp v18, v96, v18 quad_perm:[2,2,2,2] row_mask:0xf bank_mask:0xf
	s_nop 1
	v_add_f32_dpp v18, v100, v18 quad_perm:[2,2,2,2] row_mask:0xf bank_mask:0xf
	s_nop 1
	v_add_f32_dpp v18, v104, v18 quad_perm:[2,2,2,2] row_mask:0xf bank_mask:0xf
	s_nop 1
	v_add_f32_dpp v18, v108, v18 quad_perm:[2,2,2,2] row_mask:0xf bank_mask:0xf
	s_nop 1
	v_add_f32_dpp v18, v96, v18 quad_perm:[3,3,3,3] row_mask:0xf bank_mask:0xf
	s_nop 1
	v_add_f32_dpp v18, v100, v18 quad_perm:[3,3,3,3] row_mask:0xf bank_mask:0xf
	s_nop 1
	v_add_f32_dpp v18, v104, v18 quad_perm:[3,3,3,3] row_mask:0xf bank_mask:0xf
	s_nop 1
	v_add_f32_dpp v18, v108, v18 quad_perm:[3,3,3,3] row_mask:0xf bank_mask:0xf
.Lpool_rs_done:
	v_fmamk_f32 v18, v18, 0x3a000000, v17
	v_rsq_f32_e32 v18, v18
	s_nop 1
	s_cmp_eq_u32 s41, 1
	s_cbranch_scc1 .Lpool_no_0
	v_readlane_b32 s53, v18, 0
	v_lshlrev_b32_e32 v20, 16, v208
	v_and_b32_e32 v21, 0xffff0000, v208
	v_lshlrev_b32_e32 v22, 16, v209
	v_and_b32_e32 v23, 0xffff0000, v209
	v_mul_f32_e32 v20, s53, v20
	v_mul_f32_e32 v21, s53, v21
	v_mul_f32_e32 v22, s53, v22
	v_mul_f32_e32 v23, s53, v23
	v_cndmask_b32_e64 v24, v32, v64, s[64:65]
	v_cndmask_b32_e64 v24, v24, v80, s[62:63]
	v_cndmask_b32_e64 v24, v24, v88, s[58:59]
	v_cndmask_b32_e64 v25, v33, v65, s[64:65]
	v_cndmask_b32_e64 v25, v25, v81, s[62:63]
	v_cndmask_b32_e64 v25, v25, v89, s[58:59]
	v_cndmask_b32_e64 v26, v34, v66, s[64:65]
	v_cndmask_b32_e64 v26, v26, v82, s[62:63]
	v_cndmask_b32_e64 v26, v26, v90, s[58:59]
	v_cndmask_b32_e64 v27, v35, v67, s[64:65]
	v_cndmask_b32_e64 v27, v27, v83, s[62:63]
	v_cndmask_b32_e64 v27, v27, v91, s[58:59]
	v_pk_fma_f32 v[28:29], v[8:9], v[20:21], v[24:25] neg_lo:[0,0,1] neg_hi:[0,0,1]
	v_pk_fma_f32 v[30:31], v[10:11], v[22:23], v[26:27] neg_lo:[0,0,1] neg_hi:[0,0,1]
	v_pk_mul_f32 v[32:33], v[8:9], v[20:21]
	v_pk_mul_f32 v[34:35], v[10:11], v[22:23]
	v_pk_add_f32 v[12:13], v[12:13], v[28:29]
	v_pk_add_f32 v[14:15], v[14:15], v[30:31]
	s_add_i32 s43, s43, 1
	s_cmp_gt_i32 s43, s15
	s_cbranch_scc1 .Lpool_ic_0
	v_cvt_f32_i32_e32 v112, s43
	v_div_scale_f32 v113, s[98:99], v112, v112, 1.0
	v_rcp_f32_e32 v114, v113
	s_nop 0
	v_fma_f32 v115, -v113, v114, 1.0
	v_fmac_f32_e32 v114, v115, v114
	v_div_scale_f32 v115, vcc, 1.0, v112, 1.0
	v_mul_f32_e32 v116, v115, v114
	v_fma_f32 v117, -v113, v116, v115
	v_fmac_f32_e32 v116, v117, v114
	v_fma_f32 v113, -v113, v116, v115
	v_div_fmas_f32 v113, v113, v114, v116
	v_div_fixup_f32 v16, v113, v112, 1.0
.Lpool_ic_0:
	v_pk_fma_f32 v[28:29], v[16:17], v[12:13], v[32:33] op_sel_hi:[0,1,1] neg_lo:[0,0,1] neg_hi:[0,0,1]
	v_pk_fma_f32 v[30:31], v[16:17], v[14:15], v[34:35] op_sel_hi:[0,1,1] neg_lo:[0,0,1] neg_hi:[0,0,1]
	v_cvt_pk_bf16_f32 v28, v28, v29
	v_cvt_pk_bf16_f32 v29, v30, v31
	global_store_dwordx2 v4, v[28:29], s[2:3]
	s_add_u32 s2, s2, 0x1000
	s_addc_u32 s3, s3, 0
.Lpool_no_0:
	v_readlane_b32 s53, v18, 4
	v_lshlrev_b32_e32 v20, 16, v210
	v_and_b32_e32 v21, 0xffff0000, v210
	v_lshlrev_b32_e32 v22, 16, v211
	v_and_b32_e32 v23, 0xffff0000, v211
	v_mul_f32_e32 v20, s53, v20
	v_mul_f32_e32 v21, s53, v21
	v_mul_f32_e32 v22, s53, v22
	v_mul_f32_e32 v23, s53, v23
	v_cndmask_b32_e64 v24, v36, v68, s[64:65]
	v_cndmask_b32_e64 v24, v24, v84, s[62:63]
	v_cndmask_b32_e64 v24, v24, v92, s[58:59]
	v_cndmask_b32_e64 v25, v37, v69, s[64:65]
	v_cndmask_b32_e64 v25, v25, v85, s[62:63]
	v_cndmask_b32_e64 v25, v25, v93, s[58:59]
	v_cndmask_b32_e64 v26, v38, v70, s[64:65]
	v_cndmask_b32_e64 v26, v26, v86, s[62:63]
	v_cndmask_b32_e64 v26, v26, v94, s[58:59]
	v_cndmask_b32_e64 v27, v39, v71, s[64:65]
	v_cndmask_b32_e64 v27, v27, v87, s[62:63]
	v_cndmask_b32_e64 v27, v27, v95, s[58:59]
	v_pk_fma_f32 v[28:29], v[8:9], v[20:21], v[24:25] neg_lo:[0,0,1] neg_hi:[0,0,1]
	v_pk_fma_f32 v[30:31], v[10:11], v[22:23], v[26:27] neg_lo:[0,0,1] neg_hi:[0,0,1]
	v_pk_mul_f32 v[36:37], v[8:9], v[20:21]
	v_pk_mul_f32 v[38:39], v[10:11], v[22:23]
	v_pk_add_f32 v[12:13], v[12:13], v[28:29]
	v_pk_add_f32 v[14:15], v[14:15], v[30:31]
	s_cmp_eq_u32 s41, 1
	s_cbranch_scc1 .Lpool_no_1
	s_add_i32 s43, s43, 1
	s_cmp_gt_i32 s43, s15
	s_cbranch_scc1 .Lpool_ic_1
	v_cvt_f32_i32_e32 v112, s43
	v_div_scale_f32 v113, s[98:99], v112, v112, 1.0
	v_rcp_f32_e32 v114, v113
	s_nop 0
	v_fma_f32 v115, -v113, v114, 1.0
	v_fmac_f32_e32 v114, v115, v114
	v_div_scale_f32 v115, vcc, 1.0, v112, 1.0
	v_mul_f32_e32 v116, v115, v114
	v_fma_f32 v117, -v113, v116, v115
	v_fmac_f32_e32 v116, v117, v114
	v_fma_f32 v113, -v113, v116, v115
	v_div_fmas_f32 v113, v113, v114, v116
	v_div_fixup_f32 v16, v113, v112, 1.0
; __device__ __forceinline__ unsigned cvt_pk_bf16(float lo, float hi) { unsigned r; asm volatile("v_cvt_pk_bf16_f32 %0, %1, %2" : "=v"(r) : "v"(lo), "v"(hi)); return r; }
; __device__ __forceinline__ float row_scale_any(const float* ssq, const float* ssqS, int row) { return row < MP ? pg8::row_scale(ssq, row) : sk::row_scale_s(ssqS, row - MP); }
; __device__ __forceinline__ f32x4 ldx4(const bf16* p) { const u32x2 w = *(const u32x2*)p; return (f32x4){__uint_as_float(w.x << 16), __uint_as_float(w.x & 0xffff0000u), __uint_as_float(w.y << 16), __uint_as_float(w.y & 0xffff0000u)}; }
; template <int W> ...
;     ...
;         for (int i = 0; i < 16; ++i) { const int r = 16 * blk + i, row = xrow0 + r; const float rs = row_scale_any(ssq, ssqS, row);
;             const f32x4 val = ldx4(X + (size_t)row * D + c4) * rs * gv;
;             wsum += val - ring[(i - W + 16) & 15]; ring[i] = val;
;             const int cnt = (pos0 + r + 1) < W ? (pos0 + r + 1) : W; const float ic = 1.0f / (float)cnt;
;             const f32x4 pv = wsum * ic - val;
;             u32x2 pw; pw.x = cvt_pk_bf16(pv[0], pv[1]); pw.y = cvt_pk_bf16(pv[2], pv[3]);
;             *(u32x2*)(P + (size_t)row * D + c4) = pw;
;             if (newpool && r >= np_first) *(f32x4*)(newpool + (size_t)(r - np_first) * D + c4) = val; }
.Lpool_ic_1:
	v_pk_fma_f32 v[28:29], v[16:17], v[12:13], v[36:37] op_sel_hi:[0,1,1] neg_lo:[0,0,1] neg_hi:[0,0,1]
	v_pk_fma_f32 v[30:31], v[16:17], v[14:15], v[38:39] op_sel_hi:[0,1,1] neg_lo:[0,0,1] neg_hi:[0,0,1]
	v_cvt_pk_bf16_f32 v28, v28, v29
	v_cvt_pk_bf16_f32 v29, v30, v31
	global_store_dwordx2 v4, v[28:29], s[2:3]
	s_add_u32 s2, s2, 0x1000
	s_addc_u32 s3, s3, 0
.Lpool_no_1:
	v_readlane_b32 s53, v18, 8
	v_lshlrev_b32_e32 v20, 16, v212
	v_and_b32_e32 v21, 0xffff0000, v212
	v_lshlrev_b32_e32 v22, 16, v213
	v_and_b32_e32 v23, 0xffff0000, v213
	v_mul_f32_e32 v20, s53, v20
	v_mul_f32_e32 v21, s53, v21
	v_mul_f32_e32 v22, s53, v22
	v_mul_f32_e32 v23, s53, v23
	v_cndmask_b32_e64 v24, v40, v72, s[64:65]
	v_cndmask_b32_e64 v24, v24, v88, s[62:63]
	v_cndmask_b32_e64 v24, v24, v32, s[58:59]
	v_cndmask_b32_e64 v25, v41, v73, s[64:65]
	v_cndmask_b32_e64 v25, v25, v89, s[62:63]
	v_cndmask_b32_e64 v25, v25, v33, s[58:59]
	v_cndmask_b32_e64 v26, v42, v74, s[64:65]
	v_cndmask_b32_e64 v26, v26, v90, s[62:63]
	v_cndmask_b32_e64 v26, v26, v34, s[58:59]
	v_cndmask_b32_e64 v27, v43, v75, s[64:65]
	v_cndmask_b32_e64 v27, v27, v91, s[62:63]
	v_cndmask_b32_e64 v27, v27, v35, s[58:59]
	v_pk_fma_f32 v[28:29], v[8:9], v[20:21], v[24:25] neg_lo:[0,0,1] neg_hi:[0,0,1]
	v_pk_fma_f32 v[30:31], v[10:11], v[22:23], v[26:27] neg_lo:[0,0,1] neg_hi:[0,0,1]
	v_pk_mul_f32 v[40:41], v[8:9], v[20:21]
	v_pk_mul_f32 v[42:43], v[10:11], v[22:23]
	v_pk_add_f32 v[12:13], v[12:13], v[28:29]
	v_pk_add_f32 v[14:15], v[14:15], v[30:31]
	s_cmp_eq_u32 s41, 1
	s_cbranch_scc1 .Lpool_no_2
	s_add_i32 s43, s43, 1
	s_cmp_gt_i32 s43, s15
	s_cbranch_scc1 .Lpool_ic_2
	v_cvt_f32_i32_e32 v112, s43
	v_div_scale_f32 v113, s[98:99], v112, v112, 1.0
	v_rcp_f32_e32 v114, v113
	s_nop 0
	v_fma_f32 v115, -v113, v114, 1.0
	v_fmac_f32_e32 v114, v115, v114
	v_div_scale_f32 v115, vcc, 1.0, v112, 1.0
	v_mul_f32_e32 v116, v115, v114
	v_fma_f32 v117, -v113, v116, v115
	v_fmac_f32_e32 v116, v117, v114
	v_fma_f32 v113, -v113, v116, v115
	v_div_fmas_f32 v113, v113, v114, v116
	v_div_fixup_f32 v16, v113, v112, 1.0
.Lpool_ic_2:
	v_pk_fma_f32 v[28:29], v[16:17], v[12:13], v[40:41] op_sel_hi:[0,1,1] neg_lo:[0,0,1] neg_hi:[0,0,1]
	v_pk_fma_f32 v[30:31], v[16:17], v[14:15], v[42:43] op_sel_hi:[0,1,1] neg_lo:[0,0,1] neg_hi:[0,0,1]
	v_cvt_pk_bf16_f32 v28, v28, v29
	v_cvt_pk_bf16_f32 v29, v30, v31
	global_store_dwordx2 v4, v[28:29], s[2:3]
	s_add_u32 s2, s2, 0x1000
	s_addc_u32 s3, s3, 0
.Lpool_no_2:
	v_readlane_b32 s53, v18, 12
	v_lshlrev_b32_e32 v20, 16, v214
	v_and_b32_e32 v21, 0xffff0000, v214
	v_lshlrev_b32_e32 v22, 16, v215
	v_and_b32_e32 v23, 0xffff0000, v215
	v_mul_f32_e32 v20, s53, v20
	v_mul_f32_e32 v21, s53, v21
	v_mul_f32_e32 v22, s53, v22
	v_mul_f32_e32 v23, s53, v23
	v_cndmask_b32_e64 v24, v44, v76, s[64:65]
	v_cndmask_b32_e64 v24, v24, v92, s[62:63]
	v_cndmask_b32_e64 v24, v24, v36, s[58:59]
	v_cndmask_b32_e64 v25, v45, v77, s[64:65]
	v_cndmask_b32_e64 v25, v25, v93, s[62:63]
	v_cndmask_b32_e64 v25, v25, v37, s[58:59]
	v_cndmask_b32_e64 v26, v46, v78, s[64:65]
	v_cndmask_b32_e64 v26, v26, v94, s[62:63]
	v_cndmask_b32_e64 v26, v26, v38, s[58:59]
	v_cndmask_b32_e64 v27, v47, v79, s[64:65]
	v_cndmask_b32_e64 v27, v27, v95, s[62:63]
	v_cndmask_b32_e64 v27, v27, v39, s[58:59]
	v_pk_fma_f32 v[28:29], v[8:9], v[20:21], v[24:25] neg_lo:[0,0,1] neg_hi:[0,0,1]
	v_pk_fma_f32 v[30:31], v[10:11], v[22:23], v[26:27] neg_lo:[0,0,1] neg_hi:[0,0,1]
	v_pk_mul_f32 v[44:45], v[8:9], v[20:21]
	v_pk_mul_f32 v[46:47], v[10:11], v[22:23]
	v_pk_add_f32 v[12:13], v[12:13], v[28:29]
	v_pk_add_f32 v[14:15], v[14:15], v[30:31]
	s_cmp_eq_u32 s41, 1
	s_cbranch_scc1 .Lpool_no_3
	s_add_i32 s43, s43, 1
	s_cmp_gt_i32 s43, s15
	s_cbranch_scc1 .Lpool_ic_3
	v_cvt_f32_i32_e32 v112, s43
	v_div_scale_f32 v113, s[98:99], v112, v112, 1.0
	v_rcp_f32_e32 v114, v113
	s_nop 0
	v_fma_f32 v115, -v113, v114, 1.0
	v_fmac_f32_e32 v114, v115, v114
	v_div_scale_f32 v115, vcc, 1.0, v112, 1.0
	v_mul_f32_e32 v116, v115, v114
	v_fma_f32 v117, -v113, v116, v115
	v_fmac_f32_e32 v116, v117, v114
	v_fma_f32 v113, -v113, v116, v115
	v_div_fmas_f32 v113, v113, v114, v116
	v_div_fixup_f32 v16, v113, v112, 1.0
.Lpool_ic_3:
	v_pk_fma_f32 v[28:29], v[16:17], v[12:13], v[44:45] op_sel_hi:[0,1,1] neg_lo:[0,0,1] neg_hi:[0,0,1]
	v_pk_fma_f32 v[30:31], v[16:17], v[14:15], v[46:47] op_sel_hi:[0,1,1] neg_lo:[0,0,1] neg_hi:[0,0,1]
	v_cvt_pk_bf16_f32 v28, v28, v29
	v_cvt_pk_bf16_f32 v29, v30, v31
	global_store_dwordx2 v4, v[28:29], s[2:3]
	s_add_u32 s2, s2, 0x1000
	s_addc_u32 s3, s3, 0
.Lpool_no_3:
	v_readlane_b32 s53, v18, 16
	v_lshlrev_b32_e32 v20, 16, v216
	v_and_b32_e32 v21, 0xffff0000, v216
	v_lshlrev_b32_e32 v22, 16, v217
	v_and_b32_e32 v23, 0xffff0000, v217
	v_mul_f32_e32 v20, s53, v20
	v_mul_f32_e32 v21, s53, v21
	v_mul_f32_e32 v22, s53, v22
	v_mul_f32_e32 v23, s53, v23
	v_cndmask_b32_e64 v24, v48, v80, s[64:65]
	v_cndmask_b32_e64 v24, v24, v32, s[62:63]
	v_cndmask_b32_e64 v24, v24, v40, s[58:59]
	v_cndmask_b32_e64 v25, v49, v81, s[64:65]
	v_cndmask_b32_e64 v25, v25, v33, s[62:63]
	v_cndmask_b32_e64 v25, v25, v41, s[58:59]
	v_cndmask_b32_e64 v26, v50, v82, s[64:65]
	v_cndmask_b32_e64 v26, v26, v34, s[62:63]
	v_cndmask_b32_e64 v26, v26, v42, s[58:59]
	v_cndmask_b32_e64 v27, v51, v83, s[64:65]
	v_cndmask_b32_e64 v27, v27, v35, s[62:63]
	v_cndmask_b32_e64 v27, v27, v43, s[58:59]
	v_pk_fma_f32 v[28:29], v[8:9], v[20:21], v[24:25] neg_lo:[0,0,1] neg_hi:[0,0,1]
	v_pk_fma_f32 v[30:31], v[10:11], v[22:23], v[26:27] neg_lo:[0,0,1] neg_hi:[0,0,1]
	v_pk_mul_f32 v[48:49], v[8:9], v[20:21]
	v_pk_mul_f32 v[50:51], v[10:11], v[22:23]
	v_pk_add_f32 v[12:13], v[12:13], v[28:29]
	v_pk_add_f32 v[14:15], v[14:15], v[30:31]
	s_cmp_eq_u32 s41, 1
	s_cbranch_scc1 .Lpool_no_4
	s_add_i32 s43, s43, 1
	s_cmp_gt_i32 s43, s15
	s_cbranch_scc1 .Lpool_ic_4
	v_cvt_f32_i32_e32 v112, s43
	v_div_scale_f32 v113, s[98:99], v112, v112, 1.0
	v_rcp_f32_e32 v114, v113
	s_nop 0
	v_fma_f32 v115, -v113, v114, 1.0
	v_fmac_f32_e32 v114, v115, v114
	v_div_scale_f32 v115, vcc, 1.0, v112, 1.0
	v_mul_f32_e32 v116, v115, v114
	v_fma_f32 v117, -v113, v116, v115
	v_fmac_f32_e32 v116, v117, v114
	v_fma_f32 v113, -v113, v116, v115
	v_div_fmas_f32 v113, v113, v114, v116
	v_div_fixup_f32 v16, v113, v112, 1.0
; __device__ __forceinline__ unsigned cvt_pk_bf16(float lo, float hi) { unsigned r; asm volatile("v_cvt_pk_bf16_f32 %0, %1, %2" : "=v"(r) : "v"(lo), "v"(hi)); return r; }
; __device__ __forceinline__ float row_scale_any(const float* ssq, const float* ssqS, int row) { return row < MP ? pg8::row_scale(ssq, row) : sk::row_scale_s(ssqS, row - MP); }
; __device__ __forceinline__ f32x4 ldx4(const bf16* p) { const u32x2 w = *(const u32x2*)p; return (f32x4){__uint_as_float(w.x << 16), __uint_as_float(w.x & 0xffff0000u), __uint_as_float(w.y << 16), __uint_as_float(w.y & 0xffff0000u)}; }
; template <int W> ...
;     ...
;         for (int i = 0; i < 16; ++i) { const int r = 16 * blk + i, row = xrow0 + r; const float rs = row_scale_any(ssq, ssqS, row);
;             const f32x4 val = ldx4(X + (size_t)row * D + c4) * rs * gv;
;             wsum += val - ring[(i - W + 16) & 15]; ring[i] = val;
;             const int cnt = (pos0 + r + 1) < W ? (pos0 + r + 1) : W; const float ic = 1.0f / (float)cnt;
;             const f32x4 pv = wsum * ic - val;
;             u32x2 pw; pw.x = cvt_pk_bf16(pv[0], pv[1]); pw.y = cvt_pk_bf16(pv[2], pv[3]);
;             *(u32x2*)(P + (size_t)row * D + c4) = pw;
;             if (newpool && r >= np_first) *(f32x4*)(newpool + (size_t)(r - np_first) * D + c4) = val; }
.Lpool_ic_4:
	v_pk_fma_f32 v[28:29], v[16:17], v[12:13], v[48:49] op_sel_hi:[0,1,1] neg_lo:[0,0,1] neg_hi:[0,0,1]
	v_pk_fma_f32 v[30:31], v[16:17], v[14:15], v[50:51] op_sel_hi:[0,1,1] neg_lo:[0,0,1] neg_hi:[0,0,1]
	v_cvt_pk_bf16_f32 v28, v28, v29
	v_cvt_pk_bf16_f32 v29, v30, v31
	global_store_dwordx2 v4, v[28:29], s[2:3]
	s_add_u32 s2, s2, 0x1000
	s_addc_u32 s3, s3, 0
.Lpool_no_4:
	v_readlane_b32 s53, v18, 20
	v_lshlrev_b32_e32 v20, 16, v218
	v_and_b32_e32 v21, 0xffff0000, v218
	v_lshlrev_b32_e32 v22, 16, v219
	v_and_b32_e32 v23, 0xffff0000, v219
	v_mul_f32_e32 v20, s53, v20
	v_mul_f32_e32 v21, s53, v21
	v_mul_f32_e32 v22, s53, v22
	v_mul_f32_e32 v23, s53, v23
	v_cndmask_b32_e64 v24, v52, v84, s[64:65]
	v_cndmask_b32_e64 v24, v24, v36, s[62:63]
	v_cndmask_b32_e64 v24, v24, v44, s[58:59]
	v_cndmask_b32_e64 v25, v53, v85, s[64:65]
	v_cndmask_b32_e64 v25, v25, v37, s[62:63]
	v_cndmask_b32_e64 v25, v25, v45, s[58:59]
	v_cndmask_b32_e64 v26, v54, v86, s[64:65]
	v_cndmask_b32_e64 v26, v26, v38, s[62:63]
	v_cndmask_b32_e64 v26, v26, v46, s[58:59]
	v_cndmask_b32_e64 v27, v55, v87, s[64:65]
	v_cndmask_b32_e64 v27, v27, v39, s[62:63]
	v_cndmask_b32_e64 v27, v27, v47, s[58:59]
	v_pk_fma_f32 v[28:29], v[8:9], v[20:21], v[24:25] neg_lo:[0,0,1] neg_hi:[0,0,1]
	v_pk_fma_f32 v[30:31], v[10:11], v[22:23], v[26:27] neg_lo:[0,0,1] neg_hi:[0,0,1]
	v_pk_mul_f32 v[52:53], v[8:9], v[20:21]
	v_pk_mul_f32 v[54:55], v[10:11], v[22:23]
	v_pk_add_f32 v[12:13], v[12:13], v[28:29]
	v_pk_add_f32 v[14:15], v[14:15], v[30:31]
	s_cmp_eq_u32 s41, 1
	s_cbranch_scc1 .Lpool_no_5
	s_add_i32 s43, s43, 1
	s_cmp_gt_i32 s43, s15
	s_cbranch_scc1 .Lpool_ic_5
	v_cvt_f32_i32_e32 v112, s43
	v_div_scale_f32 v113, s[98:99], v112, v112, 1.0
	v_rcp_f32_e32 v114, v113
	s_nop 0
	v_fma_f32 v115, -v113, v114, 1.0
	v_fmac_f32_e32 v114, v115, v114
	v_div_scale_f32 v115, vcc, 1.0, v112, 1.0
	v_mul_f32_e32 v116, v115, v114
	v_fma_f32 v117, -v113, v116, v115
	v_fmac_f32_e32 v116, v117, v114
	v_fma_f32 v113, -v113, v116, v115
	v_div_fmas_f32 v113, v113, v114, v116
	v_div_fixup_f32 v16, v113, v112, 1.0
.Lpool_ic_5:
	v_pk_fma_f32 v[28:29], v[16:17], v[12:13], v[52:53] op_sel_hi:[0,1,1] neg_lo:[0,0,1] neg_hi:[0,0,1]
	v_pk_fma_f32 v[30:31], v[16:17], v[14:15], v[54:55] op_sel_hi:[0,1,1] neg_lo:[0,0,1] neg_hi:[0,0,1]
	v_cvt_pk_bf16_f32 v28, v28, v29
	v_cvt_pk_bf16_f32 v29, v30, v31
	global_store_dwordx2 v4, v[28:29], s[2:3]
	s_add_u32 s2, s2, 0x1000
	s_addc_u32 s3, s3, 0
.Lpool_no_5:
	v_readlane_b32 s53, v18, 24
	v_lshlrev_b32_e32 v20, 16, v220
	v_and_b32_e32 v21, 0xffff0000, v220
	v_lshlrev_b32_e32 v22, 16, v221
	v_and_b32_e32 v23, 0xffff0000, v221
	v_mul_f32_e32 v20, s53, v20
	v_mul_f32_e32 v21, s53, v21
	v_mul_f32_e32 v22, s53, v22
	v_mul_f32_e32 v23, s53, v23
	v_cndmask_b32_e64 v24, v56, v88, s[64:65]
	v_cndmask_b32_e64 v24, v24, v40, s[62:63]
	v_cndmask_b32_e64 v24, v24, v48, s[58:59]
	v_cndmask_b32_e64 v25, v57, v89, s[64:65]
	v_cndmask_b32_e64 v25, v25, v41, s[62:63]
	v_cndmask_b32_e64 v25, v25, v49, s[58:59]
	v_cndmask_b32_e64 v26, v58, v90, s[64:65]
	v_cndmask_b32_e64 v26, v26, v42, s[62:63]
	v_cndmask_b32_e64 v26, v26, v50, s[58:59]
	v_cndmask_b32_e64 v27, v59, v91, s[64:65]
	v_cndmask_b32_e64 v27, v27, v43, s[62:63]
	v_cndmask_b32_e64 v27, v27, v51, s[58:59]
	v_pk_fma_f32 v[28:29], v[8:9], v[20:21], v[24:25] neg_lo:[0,0,1] neg_hi:[0,0,1]
	v_pk_fma_f32 v[30:31], v[10:11], v[22:23], v[26:27] neg_lo:[0,0,1] neg_hi:[0,0,1]
	v_pk_mul_f32 v[56:57], v[8:9], v[20:21]
	v_pk_mul_f32 v[58:59], v[10:11], v[22:23]
	v_pk_add_f32 v[12:13], v[12:13], v[28:29]
	v_pk_add_f32 v[14:15], v[14:15], v[30:31]
	s_cmp_eq_u32 s41, 1
	s_cbranch_scc1 .Lpool_no_6
	s_add_i32 s43, s43, 1
	s_cmp_gt_i32 s43, s15
	s_cbranch_scc1 .Lpool_ic_6
	v_cvt_f32_i32_e32 v112, s43
	v_div_scale_f32 v113, s[98:99], v112, v112, 1.0
	v_rcp_f32_e32 v114, v113
	s_nop 0
	v_fma_f32 v115, -v113, v114, 1.0
	v_fmac_f32_e32 v114, v115, v114
	v_div_scale_f32 v115, vcc, 1.0, v112, 1.0
	v_mul_f32_e32 v116, v115, v114
	v_fma_f32 v117, -v113, v116, v115
	v_fmac_f32_e32 v116, v117, v114
	v_fma_f32 v113, -v113, v116, v115
	v_div_fmas_f32 v113, v113, v114, v116
	v_div_fixup_f32 v16, v113, v112, 1.0
.Lpool_ic_6:
	v_pk_fma_f32 v[28:29], v[16:17], v[12:13], v[56:57] op_sel_hi:[0,1,1] neg_lo:[0,0,1] neg_hi:[0,0,1]
	v_pk_fma_f32 v[30:31], v[16:17], v[14:15], v[58:59] op_sel_hi:[0,1,1] neg_lo:[0,0,1] neg_hi:[0,0,1]
	v_cvt_pk_bf16_f32 v28, v28, v29
	v_cvt_pk_bf16_f32 v29, v30, v31
	global_store_dwordx2 v4, v[28:29], s[2:3]
	s_add_u32 s2, s2, 0x1000
	s_addc_u32 s3, s3, 0
.Lpool_no_6:
	v_readlane_b32 s53, v18, 28
	v_lshlrev_b32_e32 v20, 16, v222
	v_and_b32_e32 v21, 0xffff0000, v222
	v_lshlrev_b32_e32 v22, 16, v223
	v_and_b32_e32 v23, 0xffff0000, v223
	v_mul_f32_e32 v20, s53, v20
	v_mul_f32_e32 v21, s53, v21
	v_mul_f32_e32 v22, s53, v22
	v_mul_f32_e32 v23, s53, v23
	v_cndmask_b32_e64 v24, v60, v92, s[64:65]
	v_cndmask_b32_e64 v24, v24, v44, s[62:63]
	v_cndmask_b32_e64 v24, v24, v52, s[58:59]
	v_cndmask_b32_e64 v25, v61, v93, s[64:65]
	v_cndmask_b32_e64 v25, v25, v45, s[62:63]
	v_cndmask_b32_e64 v25, v25, v53, s[58:59]
	v_cndmask_b32_e64 v26, v62, v94, s[64:65]
	v_cndmask_b32_e64 v26, v26, v46, s[62:63]
	v_cndmask_b32_e64 v26, v26, v54, s[58:59]
	v_cndmask_b32_e64 v27, v63, v95, s[64:65]
	v_cndmask_b32_e64 v27, v27, v47, s[62:63]
	v_cndmask_b32_e64 v27, v27, v55, s[58:59]
	v_pk_fma_f32 v[28:29], v[8:9], v[20:21], v[24:25] neg_lo:[0,0,1] neg_hi:[0,0,1]
	v_pk_fma_f32 v[30:31], v[10:11], v[22:23], v[26:27] neg_lo:[0,0,1] neg_hi:[0,0,1]
	v_pk_mul_f32 v[60:61], v[8:9], v[20:21]
	v_pk_mul_f32 v[62:63], v[10:11], v[22:23]
	v_pk_add_f32 v[12:13], v[12:13], v[28:29]
	v_pk_add_f32 v[14:15], v[14:15], v[30:31]
	s_cmp_eq_u32 s41, 1
	s_cbranch_scc1 .Lpool_no_7
	s_add_i32 s43, s43, 1
	s_cmp_gt_i32 s43, s15
	s_cbranch_scc1 .Lpool_ic_7
	v_cvt_f32_i32_e32 v112, s43
	v_div_scale_f32 v113, s[98:99], v112, v112, 1.0
	v_rcp_f32_e32 v114, v113
	s_nop 0
	v_fma_f32 v115, -v113, v114, 1.0
	v_fmac_f32_e32 v114, v115, v114
	v_div_scale_f32 v115, vcc, 1.0, v112, 1.0
	v_mul_f32_e32 v116, v115, v114
	v_fma_f32 v117, -v113, v116, v115
	v_fmac_f32_e32 v116, v117, v114
	v_fma_f32 v113, -v113, v116, v115
	v_div_fmas_f32 v113, v113, v114, v116
	v_div_fixup_f32 v16, v113, v112, 1.0
; __device__ __forceinline__ unsigned cvt_pk_bf16(float lo, float hi) { unsigned r; asm volatile("v_cvt_pk_bf16_f32 %0, %1, %2" : "=v"(r) : "v"(lo), "v"(hi)); return r; }
; __device__ __forceinline__ float row_scale_any(const float* ssq, const float* ssqS, int row) { return row < MP ? pg8::row_scale(ssq, row) : sk::row_scale_s(ssqS, row - MP); }
; __device__ __forceinline__ f32x4 ldx4(const bf16* p) { const u32x2 w = *(const u32x2*)p; return (f32x4){__uint_as_float(w.x << 16), __uint_as_float(w.x & 0xffff0000u), __uint_as_float(w.y << 16), __uint_as_float(w.y & 0xffff0000u)}; }
; template <int W> ...
;     ...
;         for (int i = 0; i < 16; ++i) { const int r = 16 * blk + i, row = xrow0 + r; const float rs = row_scale_any(ssq, ssqS, row);
;             const f32x4 val = ldx4(X + (size_t)row * D + c4) * rs * gv;
;             wsum += val - ring[(i - W + 16) & 15]; ring[i] = val;
;             const int cnt = (pos0 + r + 1) < W ? (pos0 + r + 1) : W; const float ic = 1.0f / (float)cnt;
;             const f32x4 pv = wsum * ic - val;
;             u32x2 pw; pw.x = cvt_pk_bf16(pv[0], pv[1]); pw.y = cvt_pk_bf16(pv[2], pv[3]);
;             *(u32x2*)(P + (size_t)row * D + c4) = pw;
;             if (newpool && r >= np_first) *(f32x4*)(newpool + (size_t)(r - np_first) * D + c4) = val; }
.Lpool_ic_7:
	v_pk_fma_f32 v[28:29], v[16:17], v[12:13], v[60:61] op_sel_hi:[0,1,1] neg_lo:[0,0,1] neg_hi:[0,0,1]
	v_pk_fma_f32 v[30:31], v[16:17], v[14:15], v[62:63] op_sel_hi:[0,1,1] neg_lo:[0,0,1] neg_hi:[0,0,1]
	v_cvt_pk_bf16_f32 v28, v28, v29
	v_cvt_pk_bf16_f32 v29, v30, v31
	global_store_dwordx2 v4, v[28:29], s[2:3]
	s_add_u32 s2, s2, 0x1000
	s_addc_u32 s3, s3, 0
.Lpool_no_7:
	v_readlane_b32 s53, v18, 32
	v_lshlrev_b32_e32 v20, 16, v224
	v_and_b32_e32 v21, 0xffff0000, v224
	v_lshlrev_b32_e32 v22, 16, v225
	v_and_b32_e32 v23, 0xffff0000, v225
	v_mul_f32_e32 v20, s53, v20
	v_mul_f32_e32 v21, s53, v21
	v_mul_f32_e32 v22, s53, v22
	v_mul_f32_e32 v23, s53, v23
	v_cndmask_b32_e64 v24, v64, v32, s[64:65]
	v_cndmask_b32_e64 v24, v24, v48, s[62:63]
	v_cndmask_b32_e64 v24, v24, v56, s[58:59]
	v_cndmask_b32_e64 v25, v65, v33, s[64:65]
	v_cndmask_b32_e64 v25, v25, v49, s[62:63]
	v_cndmask_b32_e64 v25, v25, v57, s[58:59]
	v_cndmask_b32_e64 v26, v66, v34, s[64:65]
	v_cndmask_b32_e64 v26, v26, v50, s[62:63]
	v_cndmask_b32_e64 v26, v26, v58, s[58:59]
	v_cndmask_b32_e64 v27, v67, v35, s[64:65]
	v_cndmask_b32_e64 v27, v27, v51, s[62:63]
	v_cndmask_b32_e64 v27, v27, v59, s[58:59]
	v_pk_fma_f32 v[28:29], v[8:9], v[20:21], v[24:25] neg_lo:[0,0,1] neg_hi:[0,0,1]
	v_pk_fma_f32 v[30:31], v[10:11], v[22:23], v[26:27] neg_lo:[0,0,1] neg_hi:[0,0,1]
	v_pk_mul_f32 v[64:65], v[8:9], v[20:21]
	v_pk_mul_f32 v[66:67], v[10:11], v[22:23]
	v_pk_add_f32 v[12:13], v[12:13], v[28:29]
	v_pk_add_f32 v[14:15], v[14:15], v[30:31]
	s_cmp_eq_u32 s41, 1
	s_cbranch_scc1 .Lpool_no_8
	s_add_i32 s43, s43, 1
	s_cmp_gt_i32 s43, s15
	s_cbranch_scc1 .Lpool_ic_8
	v_cvt_f32_i32_e32 v112, s43
	v_div_scale_f32 v113, s[98:99], v112, v112, 1.0
	v_rcp_f32_e32 v114, v113
	s_nop 0
	v_fma_f32 v115, -v113, v114, 1.0
	v_fmac_f32_e32 v114, v115, v114
	v_div_scale_f32 v115, vcc, 1.0, v112, 1.0
	v_mul_f32_e32 v116, v115, v114
	v_fma_f32 v117, -v113, v116, v115
	v_fmac_f32_e32 v116, v117, v114
	v_fma_f32 v113, -v113, v116, v115
	v_div_fmas_f32 v113, v113, v114, v116
	v_div_fixup_f32 v16, v113, v112, 1.0
.Lpool_ic_8:
	v_pk_fma_f32 v[28:29], v[16:17], v[12:13], v[64:65] op_sel_hi:[0,1,1] neg_lo:[0,0,1] neg_hi:[0,0,1]
	v_pk_fma_f32 v[30:31], v[16:17], v[14:15], v[66:67] op_sel_hi:[0,1,1] neg_lo:[0,0,1] neg_hi:[0,0,1]
	v_cvt_pk_bf16_f32 v28, v28, v29
	v_cvt_pk_bf16_f32 v29, v30, v31
	global_store_dwordx2 v4, v[28:29], s[2:3]
	s_add_u32 s2, s2, 0x1000
	s_addc_u32 s3, s3, 0
.Lpool_no_8:
	v_readlane_b32 s53, v18, 36
	v_lshlrev_b32_e32 v20, 16, v226
	v_and_b32_e32 v21, 0xffff0000, v226
	v_lshlrev_b32_e32 v22, 16, v227
	v_and_b32_e32 v23, 0xffff0000, v227
	v_mul_f32_e32 v20, s53, v20
	v_mul_f32_e32 v21, s53, v21
	v_mul_f32_e32 v22, s53, v22
	v_mul_f32_e32 v23, s53, v23
	v_cndmask_b32_e64 v24, v68, v36, s[64:65]
	v_cndmask_b32_e64 v24, v24, v52, s[62:63]
	v_cndmask_b32_e64 v24, v24, v60, s[58:59]
	v_cndmask_b32_e64 v25, v69, v37, s[64:65]
	v_cndmask_b32_e64 v25, v25, v53, s[62:63]
	v_cndmask_b32_e64 v25, v25, v61, s[58:59]
	v_cndmask_b32_e64 v26, v70, v38, s[64:65]
	v_cndmask_b32_e64 v26, v26, v54, s[62:63]
	v_cndmask_b32_e64 v26, v26, v62, s[58:59]
	v_cndmask_b32_e64 v27, v71, v39, s[64:65]
	v_cndmask_b32_e64 v27, v27, v55, s[62:63]
	v_cndmask_b32_e64 v27, v27, v63, s[58:59]
	v_pk_fma_f32 v[28:29], v[8:9], v[20:21], v[24:25] neg_lo:[0,0,1] neg_hi:[0,0,1]
	v_pk_fma_f32 v[30:31], v[10:11], v[22:23], v[26:27] neg_lo:[0,0,1] neg_hi:[0,0,1]
	v_pk_mul_f32 v[68:69], v[8:9], v[20:21]
	v_pk_mul_f32 v[70:71], v[10:11], v[22:23]
	v_pk_add_f32 v[12:13], v[12:13], v[28:29]
	v_pk_add_f32 v[14:15], v[14:15], v[30:31]
	s_cmp_eq_u32 s41, 1
	s_cbranch_scc1 .Lpool_no_9
	s_add_i32 s43, s43, 1
	s_cmp_gt_i32 s43, s15
	s_cbranch_scc1 .Lpool_ic_9
	v_cvt_f32_i32_e32 v112, s43
	v_div_scale_f32 v113, s[98:99], v112, v112, 1.0
	v_rcp_f32_e32 v114, v113
	s_nop 0
	v_fma_f32 v115, -v113, v114, 1.0
	v_fmac_f32_e32 v114, v115, v114
	v_div_scale_f32 v115, vcc, 1.0, v112, 1.0
	v_mul_f32_e32 v116, v115, v114
	v_fma_f32 v117, -v113, v116, v115
	v_fmac_f32_e32 v116, v117, v114
	v_fma_f32 v113, -v113, v116, v115
	v_div_fmas_f32 v113, v113, v114, v116
	v_div_fixup_f32 v16, v113, v112, 1.0
.Lpool_ic_9:
	v_pk_fma_f32 v[28:29], v[16:17], v[12:13], v[68:69] op_sel_hi:[0,1,1] neg_lo:[0,0,1] neg_hi:[0,0,1]
	v_pk_fma_f32 v[30:31], v[16:17], v[14:15], v[70:71] op_sel_hi:[0,1,1] neg_lo:[0,0,1] neg_hi:[0,0,1]
	v_cvt_pk_bf16_f32 v28, v28, v29
	v_cvt_pk_bf16_f32 v29, v30, v31
	global_store_dwordx2 v4, v[28:29], s[2:3]
	s_add_u32 s2, s2, 0x1000
	s_addc_u32 s3, s3, 0
.Lpool_no_9:
	v_readlane_b32 s53, v18, 40
	v_lshlrev_b32_e32 v20, 16, v228
	v_and_b32_e32 v21, 0xffff0000, v228
	v_lshlrev_b32_e32 v22, 16, v229
	v_and_b32_e32 v23, 0xffff0000, v229
	v_mul_f32_e32 v20, s53, v20
	v_mul_f32_e32 v21, s53, v21
	v_mul_f32_e32 v22, s53, v22
	v_mul_f32_e32 v23, s53, v23
	v_cndmask_b32_e64 v24, v72, v40, s[64:65]
	v_cndmask_b32_e64 v24, v24, v56, s[62:63]
	v_cndmask_b32_e64 v24, v24, v64, s[58:59]
	v_cndmask_b32_e64 v25, v73, v41, s[64:65]
	v_cndmask_b32_e64 v25, v25, v57, s[62:63]
	v_cndmask_b32_e64 v25, v25, v65, s[58:59]
	v_cndmask_b32_e64 v26, v74, v42, s[64:65]
	v_cndmask_b32_e64 v26, v26, v58, s[62:63]
	v_cndmask_b32_e64 v26, v26, v66, s[58:59]
	v_cndmask_b32_e64 v27, v75, v43, s[64:65]
	v_cndmask_b32_e64 v27, v27, v59, s[62:63]
	v_cndmask_b32_e64 v27, v27, v67, s[58:59]
	v_pk_fma_f32 v[28:29], v[8:9], v[20:21], v[24:25] neg_lo:[0,0,1] neg_hi:[0,0,1]
	v_pk_fma_f32 v[30:31], v[10:11], v[22:23], v[26:27] neg_lo:[0,0,1] neg_hi:[0,0,1]
	v_pk_mul_f32 v[72:73], v[8:9], v[20:21]
	v_pk_mul_f32 v[74:75], v[10:11], v[22:23]
	v_pk_add_f32 v[12:13], v[12:13], v[28:29]
	v_pk_add_f32 v[14:15], v[14:15], v[30:31]
	s_cmp_eq_u32 s41, 1
	s_cbranch_scc1 .Lpool_no_10
	s_add_i32 s43, s43, 1
	s_cmp_gt_i32 s43, s15
	s_cbranch_scc1 .Lpool_ic_10
	v_cvt_f32_i32_e32 v112, s43
	v_div_scale_f32 v113, s[98:99], v112, v112, 1.0
	v_rcp_f32_e32 v114, v113
	s_nop 0
	v_fma_f32 v115, -v113, v114, 1.0
	v_fmac_f32_e32 v114, v115, v114
	v_div_scale_f32 v115, vcc, 1.0, v112, 1.0
	v_mul_f32_e32 v116, v115, v114
	v_fma_f32 v117, -v113, v116, v115
	v_fmac_f32_e32 v116, v117, v114
	v_fma_f32 v113, -v113, v116, v115
	v_div_fmas_f32 v113, v113, v114, v116
	v_div_fixup_f32 v16, v113, v112, 1.0
; __device__ __forceinline__ unsigned cvt_pk_bf16(float lo, float hi) { unsigned r; asm volatile("v_cvt_pk_bf16_f32 %0, %1, %2" : "=v"(r) : "v"(lo), "v"(hi)); return r; }
; __device__ __forceinline__ float row_scale_any(const float* ssq, const float* ssqS, int row) { return row < MP ? pg8::row_scale(ssq, row) : sk::row_scale_s(ssqS, row - MP); }
; __device__ __forceinline__ f32x4 ldx4(const bf16* p) { const u32x2 w = *(const u32x2*)p; return (f32x4){__uint_as_float(w.x << 16), __uint_as_float(w.x & 0xffff0000u), __uint_as_float(w.y << 16), __uint_as_float(w.y & 0xffff0000u)}; }
; template <int W> ...
;     ...
;         for (int i = 0; i < 16; ++i) { const int r = 16 * blk + i, row = xrow0 + r; const float rs = row_scale_any(ssq, ssqS, row);
;             const f32x4 val = ldx4(X + (size_t)row * D + c4) * rs * gv;
;             wsum += val - ring[(i - W + 16) & 15]; ring[i] = val;
;             const int cnt = (pos0 + r + 1) < W ? (pos0 + r + 1) : W; const float ic = 1.0f / (float)cnt;
;             const f32x4 pv = wsum * ic - val;
;             u32x2 pw; pw.x = cvt_pk_bf16(pv[0], pv[1]); pw.y = cvt_pk_bf16(pv[2], pv[3]);
;             *(u32x2*)(P + (size_t)row * D + c4) = pw;
;             if (newpool && r >= np_first) *(f32x4*)(newpool + (size_t)(r - np_first) * D + c4) = val; }
.Lpool_ic_10:
	v_pk_fma_f32 v[28:29], v[16:17], v[12:13], v[72:73] op_sel_hi:[0,1,1] neg_lo:[0,0,1] neg_hi:[0,0,1]
	v_pk_fma_f32 v[30:31], v[16:17], v[14:15], v[74:75] op_sel_hi:[0,1,1] neg_lo:[0,0,1] neg_hi:[0,0,1]
	v_cvt_pk_bf16_f32 v28, v28, v29
	v_cvt_pk_bf16_f32 v29, v30, v31
	global_store_dwordx2 v4, v[28:29], s[2:3]
	s_add_u32 s2, s2, 0x1000
	s_addc_u32 s3, s3, 0
.Lpool_no_10:
	v_readlane_b32 s53, v18, 44
	v_lshlrev_b32_e32 v20, 16, v230
	v_and_b32_e32 v21, 0xffff0000, v230
	v_lshlrev_b32_e32 v22, 16, v231
	v_and_b32_e32 v23, 0xffff0000, v231
	v_mul_f32_e32 v20, s53, v20
	v_mul_f32_e32 v21, s53, v21
	v_mul_f32_e32 v22, s53, v22
	v_mul_f32_e32 v23, s53, v23
	v_cndmask_b32_e64 v24, v76, v44, s[64:65]
	v_cndmask_b32_e64 v24, v24, v60, s[62:63]
	v_cndmask_b32_e64 v24, v24, v68, s[58:59]
	v_cndmask_b32_e64 v25, v77, v45, s[64:65]
	v_cndmask_b32_e64 v25, v25, v61, s[62:63]
	v_cndmask_b32_e64 v25, v25, v69, s[58:59]
	v_cndmask_b32_e64 v26, v78, v46, s[64:65]
	v_cndmask_b32_e64 v26, v26, v62, s[62:63]
	v_cndmask_b32_e64 v26, v26, v70, s[58:59]
	v_cndmask_b32_e64 v27, v79, v47, s[64:65]
	v_cndmask_b32_e64 v27, v27, v63, s[62:63]
	v_cndmask_b32_e64 v27, v27, v71, s[58:59]
	v_pk_fma_f32 v[28:29], v[8:9], v[20:21], v[24:25] neg_lo:[0,0,1] neg_hi:[0,0,1]
	v_pk_fma_f32 v[30:31], v[10:11], v[22:23], v[26:27] neg_lo:[0,0,1] neg_hi:[0,0,1]
	v_pk_mul_f32 v[76:77], v[8:9], v[20:21]
	v_pk_mul_f32 v[78:79], v[10:11], v[22:23]
	v_pk_add_f32 v[12:13], v[12:13], v[28:29]
	v_pk_add_f32 v[14:15], v[14:15], v[30:31]
	s_cmp_eq_u32 s41, 1
	s_cbranch_scc1 .Lpool_no_11
	s_add_i32 s43, s43, 1
	s_cmp_gt_i32 s43, s15
	s_cbranch_scc1 .Lpool_ic_11
	v_cvt_f32_i32_e32 v112, s43
	v_div_scale_f32 v113, s[98:99], v112, v112, 1.0
	v_rcp_f32_e32 v114, v113
	s_nop 0
	v_fma_f32 v115, -v113, v114, 1.0
	v_fmac_f32_e32 v114, v115, v114
	v_div_scale_f32 v115, vcc, 1.0, v112, 1.0
	v_mul_f32_e32 v116, v115, v114
	v_fma_f32 v117, -v113, v116, v115
	v_fmac_f32_e32 v116, v117, v114
	v_fma_f32 v113, -v113, v116, v115
	v_div_fmas_f32 v113, v113, v114, v116
	v_div_fixup_f32 v16, v113, v112, 1.0
.Lpool_ic_11:
	v_pk_fma_f32 v[28:29], v[16:17], v[12:13], v[76:77] op_sel_hi:[0,1,1] neg_lo:[0,0,1] neg_hi:[0,0,1]
	v_pk_fma_f32 v[30:31], v[16:17], v[14:15], v[78:79] op_sel_hi:[0,1,1] neg_lo:[0,0,1] neg_hi:[0,0,1]
	v_cvt_pk_bf16_f32 v28, v28, v29
	v_cvt_pk_bf16_f32 v29, v30, v31
	global_store_dwordx2 v4, v[28:29], s[2:3]
	s_add_u32 s2, s2, 0x1000
	s_addc_u32 s3, s3, 0
.Lpool_no_11:
	v_readlane_b32 s53, v18, 48
	v_lshlrev_b32_e32 v20, 16, v232
	v_and_b32_e32 v21, 0xffff0000, v232
	v_lshlrev_b32_e32 v22, 16, v233
	v_and_b32_e32 v23, 0xffff0000, v233
	v_mul_f32_e32 v20, s53, v20
	v_mul_f32_e32 v21, s53, v21
	v_mul_f32_e32 v22, s53, v22
	v_mul_f32_e32 v23, s53, v23
	v_cndmask_b32_e64 v24, v80, v48, s[64:65]
	v_cndmask_b32_e64 v24, v24, v64, s[62:63]
	v_cndmask_b32_e64 v24, v24, v72, s[58:59]
	v_cndmask_b32_e64 v25, v81, v49, s[64:65]
	v_cndmask_b32_e64 v25, v25, v65, s[62:63]
	v_cndmask_b32_e64 v25, v25, v73, s[58:59]
	v_cndmask_b32_e64 v26, v82, v50, s[64:65]
	v_cndmask_b32_e64 v26, v26, v66, s[62:63]
	v_cndmask_b32_e64 v26, v26, v74, s[58:59]
	v_cndmask_b32_e64 v27, v83, v51, s[64:65]
	v_cndmask_b32_e64 v27, v27, v67, s[62:63]
	v_cndmask_b32_e64 v27, v27, v75, s[58:59]
	v_pk_fma_f32 v[28:29], v[8:9], v[20:21], v[24:25] neg_lo:[0,0,1] neg_hi:[0,0,1]
	v_pk_fma_f32 v[30:31], v[10:11], v[22:23], v[26:27] neg_lo:[0,0,1] neg_hi:[0,0,1]
	v_pk_mul_f32 v[80:81], v[8:9], v[20:21]
	v_pk_mul_f32 v[82:83], v[10:11], v[22:23]
	v_pk_add_f32 v[12:13], v[12:13], v[28:29]
	v_pk_add_f32 v[14:15], v[14:15], v[30:31]
	s_cmp_eq_u32 s41, 1
	s_cbranch_scc1 .Lpool_no_12
	s_add_i32 s43, s43, 1
	s_cmp_gt_i32 s43, s15
	s_cbranch_scc1 .Lpool_ic_12
	v_cvt_f32_i32_e32 v112, s43
	v_div_scale_f32 v113, s[98:99], v112, v112, 1.0
	v_rcp_f32_e32 v114, v113
	s_nop 0
	v_fma_f32 v115, -v113, v114, 1.0
	v_fmac_f32_e32 v114, v115, v114
	v_div_scale_f32 v115, vcc, 1.0, v112, 1.0
	v_mul_f32_e32 v116, v115, v114
	v_fma_f32 v117, -v113, v116, v115
	v_fmac_f32_e32 v116, v117, v114
	v_fma_f32 v113, -v113, v116, v115
	v_div_fmas_f32 v113, v113, v114, v116
	v_div_fixup_f32 v16, v113, v112, 1.0
.Lpool_ic_12:
	v_pk_fma_f32 v[28:29], v[16:17], v[12:13], v[80:81] op_sel_hi:[0,1,1] neg_lo:[0,0,1] neg_hi:[0,0,1]
	v_pk_fma_f32 v[30:31], v[16:17], v[14:15], v[82:83] op_sel_hi:[0,1,1] neg_lo:[0,0,1] neg_hi:[0,0,1]
	v_cvt_pk_bf16_f32 v28, v28, v29
	v_cvt_pk_bf16_f32 v29, v30, v31
	global_store_dwordx2 v4, v[28:29], s[2:3]
	s_add_u32 s2, s2, 0x1000
	s_addc_u32 s3, s3, 0
.Lpool_no_12:
	v_readlane_b32 s53, v18, 52
	v_lshlrev_b32_e32 v20, 16, v234
	v_and_b32_e32 v21, 0xffff0000, v234
	v_lshlrev_b32_e32 v22, 16, v235
	v_and_b32_e32 v23, 0xffff0000, v235
	v_mul_f32_e32 v20, s53, v20
	v_mul_f32_e32 v21, s53, v21
	v_mul_f32_e32 v22, s53, v22
	v_mul_f32_e32 v23, s53, v23
	v_cndmask_b32_e64 v24, v84, v52, s[64:65]
	v_cndmask_b32_e64 v24, v24, v68, s[62:63]
	v_cndmask_b32_e64 v24, v24, v76, s[58:59]
	v_cndmask_b32_e64 v25, v85, v53, s[64:65]
	v_cndmask_b32_e64 v25, v25, v69, s[62:63]
	v_cndmask_b32_e64 v25, v25, v77, s[58:59]
	v_cndmask_b32_e64 v26, v86, v54, s[64:65]
	v_cndmask_b32_e64 v26, v26, v70, s[62:63]
	v_cndmask_b32_e64 v26, v26, v78, s[58:59]
	v_cndmask_b32_e64 v27, v87, v55, s[64:65]
	v_cndmask_b32_e64 v27, v27, v71, s[62:63]
	v_cndmask_b32_e64 v27, v27, v79, s[58:59]
	v_pk_fma_f32 v[28:29], v[8:9], v[20:21], v[24:25] neg_lo:[0,0,1] neg_hi:[0,0,1]
	v_pk_fma_f32 v[30:31], v[10:11], v[22:23], v[26:27] neg_lo:[0,0,1] neg_hi:[0,0,1]
	v_pk_mul_f32 v[84:85], v[8:9], v[20:21]
	v_pk_mul_f32 v[86:87], v[10:11], v[22:23]
	v_pk_add_f32 v[12:13], v[12:13], v[28:29]
	v_pk_add_f32 v[14:15], v[14:15], v[30:31]
	s_cmp_eq_u32 s41, 1
	s_cbranch_scc1 .Lpool_no_13
	s_add_i32 s43, s43, 1
	s_cmp_gt_i32 s43, s15
	s_cbranch_scc1 .Lpool_ic_13
	v_cvt_f32_i32_e32 v112, s43
	v_div_scale_f32 v113, s[98:99], v112, v112, 1.0
	v_rcp_f32_e32 v114, v113
	s_nop 0
	v_fma_f32 v115, -v113, v114, 1.0
	v_fmac_f32_e32 v114, v115, v114
	v_div_scale_f32 v115, vcc, 1.0, v112, 1.0
	v_mul_f32_e32 v116, v115, v114
	v_fma_f32 v117, -v113, v116, v115
	v_fmac_f32_e32 v116, v117, v114
	v_fma_f32 v113, -v113, v116, v115
	v_div_fmas_f32 v113, v113, v114, v116
	v_div_fixup_f32 v16, v113, v112, 1.0
; __device__ __forceinline__ unsigned cvt_pk_bf16(float lo, float hi) { unsigned r; asm volatile("v_cvt_pk_bf16_f32 %0, %1, %2" : "=v"(r) : "v"(lo), "v"(hi)); return r; }
; __device__ __forceinline__ float row_scale_any(const float* ssq, const float* ssqS, int row) { return row < MP ? pg8::row_scale(ssq, row) : sk::row_scale_s(ssqS, row - MP); }
; template <int W> ...
;     ...
;     for (int blk = 0; blk < nt / 16; ++blk) {
; #pragma unroll
;         for (int i = 0; i < 16; ++i) { const int r = 16 * blk + i, row = xrow0 + r; const float rs = row_scale_any(ssq, ssqS, row);
;             const f32x4 val = ldx4(X + (size_t)row * D + c4) * rs * gv;
;             wsum += val - ring[(i - W + 16) & 15]; ring[i] = val;
;             const int cnt = (pos0 + r + 1) < W ? (pos0 + r + 1) : W; const float ic = 1.0f / (float)cnt;
;             const f32x4 pv = wsum * ic - val;
;             u32x2 pw; pw.x = cvt_pk_bf16(pv[0], pv[1]); pw.y = cvt_pk_bf16(pv[2], pv[3]);
;             *(u32x2*)(P + (size_t)row * D + c4) = pw;
;             if (newpool && r >= np_first) *(f32x4*)(newpool + (size_t)(r - np_first) * D + c4) = val; }
;     }
; }
; __global__ void __launch_bounds__(512, 2) fwd_kernel(Args a) {
;     ...
;                 for (int t = vcu; t < 256 + 16; t += G) {
;                     int xrow0, nt, pos0, hm, npf; const float* hist = nullptr; float* np = nullptr;
;                     if (t < 256) { xrow0 = 64 * t; nt = 64; pos0 = 64 * t; hm = t == 0 ? 1 : 0; npf = 49; if (t == 255) np = out + OFF_PL_P; }
;                     else { const int b = t - 256; xrow0 = MP + 16 * b; nt = 16; pos0 = 4096; hm = 2; hist = ap->in[I_SPL] + (size_t)b * 15 * D; npf = 1; np = out + OFF_PL_S + (size_t)b * 15 * D; }
;                     if (grp == 0) pool_tile<2>(XB, ssq_mix, sq_mix, gain, hist, hm, xrow0, nt, pos0, A0, np, npf, c4);
;                     else if (grp == 1) pool_tile<4>(XB, ssq_mix, sq_mix, gain, hist, hm, xrow0, nt, pos0, A0, np, npf, c4);
;                     else if (grp == 2) pool_tile<8>(XB, ssq_mix, sq_mix, gain, hist, hm, xrow0, nt, pos0, A0, np, npf, c4);
;                     else pool_tile<16>(XB, ssq_mix, sq_mix, gain, hist, hm, xrow0, nt, pos0, A0, np, npf, c4); } }
.Lpool_ic_13:
	v_pk_fma_f32 v[28:29], v[16:17], v[12:13], v[84:85] op_sel_hi:[0,1,1] neg_lo:[0,0,1] neg_hi:[0,0,1]
	v_pk_fma_f32 v[30:31], v[16:17], v[14:15], v[86:87] op_sel_hi:[0,1,1] neg_lo:[0,0,1] neg_hi:[0,0,1]
	v_cvt_pk_bf16_f32 v28, v28, v29
	v_cvt_pk_bf16_f32 v29, v30, v31
	global_store_dwordx2 v4, v[28:29], s[2:3]
	s_add_u32 s2, s2, 0x1000
	s_addc_u32 s3, s3, 0
.Lpool_no_13:
	v_readlane_b32 s53, v18, 56
	v_lshlrev_b32_e32 v20, 16, v236
	v_and_b32_e32 v21, 0xffff0000, v236
	v_lshlrev_b32_e32 v22, 16, v237
	v_and_b32_e32 v23, 0xffff0000, v237
	v_mul_f32_e32 v20, s53, v20
	v_mul_f32_e32 v21, s53, v21
	v_mul_f32_e32 v22, s53, v22
	v_mul_f32_e32 v23, s53, v23
	v_cndmask_b32_e64 v24, v88, v56, s[64:65]
	v_cndmask_b32_e64 v24, v24, v72, s[62:63]
	v_cndmask_b32_e64 v24, v24, v80, s[58:59]
	v_cndmask_b32_e64 v25, v89, v57, s[64:65]
	v_cndmask_b32_e64 v25, v25, v73, s[62:63]
	v_cndmask_b32_e64 v25, v25, v81, s[58:59]
	v_cndmask_b32_e64 v26, v90, v58, s[64:65]
	v_cndmask_b32_e64 v26, v26, v74, s[62:63]
	v_cndmask_b32_e64 v26, v26, v82, s[58:59]
	v_cndmask_b32_e64 v27, v91, v59, s[64:65]
	v_cndmask_b32_e64 v27, v27, v75, s[62:63]
	v_cndmask_b32_e64 v27, v27, v83, s[58:59]
	v_pk_fma_f32 v[28:29], v[8:9], v[20:21], v[24:25] neg_lo:[0,0,1] neg_hi:[0,0,1]
	v_pk_fma_f32 v[30:31], v[10:11], v[22:23], v[26:27] neg_lo:[0,0,1] neg_hi:[0,0,1]
	v_pk_mul_f32 v[88:89], v[8:9], v[20:21]
	v_pk_mul_f32 v[90:91], v[10:11], v[22:23]
	v_pk_add_f32 v[12:13], v[12:13], v[28:29]
	v_pk_add_f32 v[14:15], v[14:15], v[30:31]
	s_cmp_eq_u32 s41, 1
	s_cbranch_scc1 .Lpool_no_14
	s_add_i32 s43, s43, 1
	s_cmp_gt_i32 s43, s15
	s_cbranch_scc1 .Lpool_ic_14
	v_cvt_f32_i32_e32 v112, s43
	v_div_scale_f32 v113, s[98:99], v112, v112, 1.0
	v_rcp_f32_e32 v114, v113
	s_nop 0
	v_fma_f32 v115, -v113, v114, 1.0
	v_fmac_f32_e32 v114, v115, v114
	v_div_scale_f32 v115, vcc, 1.0, v112, 1.0
	v_mul_f32_e32 v116, v115, v114
	v_fma_f32 v117, -v113, v116, v115
	v_fmac_f32_e32 v116, v117, v114
	v_fma_f32 v113, -v113, v116, v115
	v_div_fmas_f32 v113, v113, v114, v116
	v_div_fixup_f32 v16, v113, v112, 1.0
.Lpool_ic_14:
	v_pk_fma_f32 v[28:29], v[16:17], v[12:13], v[88:89] op_sel_hi:[0,1,1] neg_lo:[0,0,1] neg_hi:[0,0,1]
	v_pk_fma_f32 v[30:31], v[16:17], v[14:15], v[90:91] op_sel_hi:[0,1,1] neg_lo:[0,0,1] neg_hi:[0,0,1]
	v_cvt_pk_bf16_f32 v28, v28, v29
	v_cvt_pk_bf16_f32 v29, v30, v31
	global_store_dwordx2 v4, v[28:29], s[2:3]
	s_add_u32 s2, s2, 0x1000
	s_addc_u32 s3, s3, 0
.Lpool_no_14:
	v_readlane_b32 s53, v18, 60
	v_lshlrev_b32_e32 v20, 16, v238
	v_and_b32_e32 v21, 0xffff0000, v238
	v_lshlrev_b32_e32 v22, 16, v239
	v_and_b32_e32 v23, 0xffff0000, v239
	v_mul_f32_e32 v20, s53, v20
	v_mul_f32_e32 v21, s53, v21
	v_mul_f32_e32 v22, s53, v22
	v_mul_f32_e32 v23, s53, v23
	v_cndmask_b32_e64 v24, v92, v60, s[64:65]
	v_cndmask_b32_e64 v24, v24, v76, s[62:63]
	v_cndmask_b32_e64 v24, v24, v84, s[58:59]
	v_cndmask_b32_e64 v25, v93, v61, s[64:65]
	v_cndmask_b32_e64 v25, v25, v77, s[62:63]
	v_cndmask_b32_e64 v25, v25, v85, s[58:59]
	v_cndmask_b32_e64 v26, v94, v62, s[64:65]
	v_cndmask_b32_e64 v26, v26, v78, s[62:63]
	v_cndmask_b32_e64 v26, v26, v86, s[58:59]
	v_cndmask_b32_e64 v27, v95, v63, s[64:65]
	v_cndmask_b32_e64 v27, v27, v79, s[62:63]
	v_cndmask_b32_e64 v27, v27, v87, s[58:59]
	v_pk_fma_f32 v[28:29], v[8:9], v[20:21], v[24:25] neg_lo:[0,0,1] neg_hi:[0,0,1]
	v_pk_fma_f32 v[30:31], v[10:11], v[22:23], v[26:27] neg_lo:[0,0,1] neg_hi:[0,0,1]
	v_pk_mul_f32 v[92:93], v[8:9], v[20:21]
	v_pk_mul_f32 v[94:95], v[10:11], v[22:23]
	v_pk_add_f32 v[12:13], v[12:13], v[28:29]
	v_pk_add_f32 v[14:15], v[14:15], v[30:31]
	s_cmp_eq_u32 s41, 1
	s_cbranch_scc1 .Lpool_no_15
	s_add_i32 s43, s43, 1
	s_cmp_gt_i32 s43, s15
	s_cbranch_scc1 .Lpool_ic_15
	v_cvt_f32_i32_e32 v112, s43
	v_div_scale_f32 v113, s[98:99], v112, v112, 1.0
	v_rcp_f32_e32 v114, v113
	s_nop 0
	v_fma_f32 v115, -v113, v114, 1.0
	v_fmac_f32_e32 v114, v115, v114
	v_div_scale_f32 v115, vcc, 1.0, v112, 1.0
	v_mul_f32_e32 v116, v115, v114
	v_fma_f32 v117, -v113, v116, v115
	v_fmac_f32_e32 v116, v117, v114
	v_fma_f32 v113, -v113, v116, v115
	v_div_fmas_f32 v113, v113, v114, v116
	v_div_fixup_f32 v16, v113, v112, 1.0
.Lpool_ic_15:
	v_pk_fma_f32 v[28:29], v[16:17], v[12:13], v[92:93] op_sel_hi:[0,1,1] neg_lo:[0,0,1] neg_hi:[0,0,1]
	v_pk_fma_f32 v[30:31], v[16:17], v[14:15], v[94:95] op_sel_hi:[0,1,1] neg_lo:[0,0,1] neg_hi:[0,0,1]
	v_cvt_pk_bf16_f32 v28, v28, v29
	v_cvt_pk_bf16_f32 v29, v30, v31
	global_store_dwordx2 v4, v[28:29], s[2:3]
	s_add_u32 s2, s2, 0x1000
	s_addc_u32 s3, s3, 0
.Lpool_no_15:
	s_add_i32 s77, s77, 16
	s_cmp_eq_u32 s41, 1
	s_cbranch_scc0 .Lpool_bend
	s_mov_b32 s41, 0
	s_branch .Lpool_blk
.Lpool_bend:
	s_sub_i32 s45, s45, 1
	s_cmp_lg_u32 s45, 0
	s_cbranch_scc1 .Lpool_blk
	s_cmp_eq_u32 s37, 1
	s_cbranch_scc0 .Lpool_tend
	global_store_dwordx4 v5, v[36:39], s[86:87]
	s_add_u32 s86, s86, 0x2000
	s_addc_u32 s87, s87, 0
	global_store_dwordx4 v5, v[40:43], s[86:87]
	s_add_u32 s86, s86, 0x2000
	s_addc_u32 s87, s87, 0
	global_store_dwordx4 v5, v[44:47], s[86:87]
	s_add_u32 s86, s86, 0x2000
	s_addc_u32 s87, s87, 0
	global_store_dwordx4 v5, v[48:51], s[86:87]
	s_add_u32 s86, s86, 0x2000
	s_addc_u32 s87, s87, 0
	global_store_dwordx4 v5, v[52:55], s[86:87]
	s_add_u32 s86, s86, 0x2000
	s_addc_u32 s87, s87, 0
	global_store_dwordx4 v5, v[56:59], s[86:87]
	s_add_u32 s86, s86, 0x2000
	s_addc_u32 s87, s87, 0
	global_store_dwordx4 v5, v[60:63], s[86:87]
	s_add_u32 s86, s86, 0x2000
	s_addc_u32 s87, s87, 0
	global_store_dwordx4 v5, v[64:67], s[86:87]
	s_add_u32 s86, s86, 0x2000
	s_addc_u32 s87, s87, 0
	global_store_dwordx4 v5, v[68:71], s[86:87]
	s_add_u32 s86, s86, 0x2000
	s_addc_u32 s87, s87, 0
	global_store_dwordx4 v5, v[72:75], s[86:87]
	s_add_u32 s86, s86, 0x2000
	s_addc_u32 s87, s87, 0
	global_store_dwordx4 v5, v[76:79], s[86:87]
	s_add_u32 s86, s86, 0x2000
	s_addc_u32 s87, s87, 0
	global_store_dwordx4 v5, v[80:83], s[86:87]
	s_add_u32 s86, s86, 0x2000
	s_addc_u32 s87, s87, 0
	global_store_dwordx4 v5, v[84:87], s[86:87]
	s_add_u32 s86, s86, 0x2000
	s_addc_u32 s87, s87, 0
	global_store_dwordx4 v5, v[88:91], s[86:87]
	s_add_u32 s86, s86, 0x2000
	s_addc_u32 s87, s87, 0
	global_store_dwordx4 v5, v[92:95], s[86:87]
.Lpool_tend:
	s_add_i32 s21, s21, s14
	s_cmpk_lt_i32 s21, 0x110
	s_cbranch_scc1 .Lpool_tile
